# adds: in-row steps of the wave sums in the finalize phase and the attention K norm done with DPP adds instead of ds_bpermute round trips (bit-identical)
# speedup vs baseline: 1.0416x; 1.0130x over previous
.LBB0_396:
	s_or_b64 exec, exec, s[4:5]
	s_load_dwordx4 s[12:15], s[16:17], 0x20
	v_lshlrev_b32_e32 v2, 2, v2
	s_waitcnt vmcnt(11)
	v_lshlrev_b32_e32 v22, 16, v10
	v_and_b32_e32 v23, 0xffff0000, v10
	v_lshlrev_b32_e32 v20, 16, v11
	s_waitcnt lgkmcnt(0)
	s_add_u32 s4, s14, s26
	s_addc_u32 s5, s15, s27
	global_load_dwordx4 v[6:9], v2, s[4:5]
	s_nop 0
	global_load_dwordx4 v[2:5], v2, s[4:5] offset:16
	v_and_b32_e32 v21, 0xffff0000, v11
	v_pk_mul_f32 v[26:27], v[22:23], v[22:23]
	v_pk_mul_f32 v[30:31], v[20:21], v[20:21]
	v_add_f32_e32 v27, v26, v27
	v_lshlrev_b32_e32 v18, 16, v12
	v_and_b32_e32 v19, 0xffff0000, v12
	v_add_f32_e32 v27, v30, v27
	v_and_b32_e32 v24, 64, v217
	v_lshlrev_b32_e32 v16, 16, v13
	v_and_b32_e32 v17, 0xffff0000, v13
	v_pk_mul_f32 v[12:13], v[18:19], v[18:19]
	v_add_f32_e32 v27, v31, v27
	v_xor_b32_e32 v29, 1, v217
	v_add_u32_e32 v24, 64, v24
	v_add_f32_e32 v12, v12, v27
	v_pk_mul_f32 v[10:11], v[16:17], v[16:17]
	v_cmp_lt_i32_e32 vcc, v29, v24
	v_add_f32_e32 v12, v13, v12
	v_add_f32_e32 v10, v10, v12
	v_cndmask_b32_e32 v29, v217, v29, vcc
	v_lshlrev_b32_e32 v26, 2, v29
	v_add_f32_e32 v29, v11, v10
	v_xor_b32_e32 v32, 2, v217
	v_cmp_lt_i32_e32 vcc, v32, v24
	v_xor_b32_e32 v34, 4, v217
	v_lshl_add_u32 v14, v14, 4, 0
	v_add_u32_e32 v25, 0x200, v15
	s_waitcnt vmcnt(0)
	v_mov_b64_e32 v[12:13], v[2:3]
	v_mov_b64_e32 v[10:11], v[0:1]
	v_cndmask_b32_e32 v11, v217, v32, vcc
	v_lshlrev_b32_e32 v27, 2, v11
	s_waitcnt lgkmcnt(0)
	s_nop 1
	v_add_f32_dpp v11, v29, v29 quad_perm:[1,0,3,2] row_mask:0xf bank_mask:0xf
	v_cmp_lt_i32_e32 vcc, v34, v24
	v_mad_u64_u32 v[32:33], s[4:5], v28, s80, v[14:15]
	s_nop 0
	v_cndmask_b32_e32 v13, v217, v34, vcc
	v_lshlrev_b32_e32 v28, 2, v13
	s_waitcnt lgkmcnt(0)
	s_nop 1
	v_add_f32_dpp v13, v11, v11 quad_perm:[2,3,0,1] row_mask:0xf bank_mask:0xf
	v_ashrrev_i32_e32 v29, 3, v25
	v_add_u32_e32 v30, s1, v29
	v_cmp_lt_i32_e64 s[4:5], -1, v30
	v_cmp_gt_i32_e64 s[6:7], s0, v30
	s_waitcnt lgkmcnt(0)
	s_nop 1
	v_add_f32_dpp v13, v13, v13 row_half_mirror row_mask:0xf bank_mask:0xf
	v_fmamk_f32 v13, v13, 0x3c800000, v166
	v_mul_f32_e32 v31, 0x4b800000, v13
	v_cmp_gt_f32_e32 vcc, s78, v13
	v_mov_b32_e32 v11, v1
	v_mov_b32_e32 v12, v1
	v_cndmask_b32_e32 v13, v13, v31, vcc
	v_rsq_f32_e32 v13, v13
	s_and_b64 s[6:7], s[4:5], s[6:7]
	v_mul_f32_e32 v31, 0x45800000, v13
	v_cndmask_b32_e32 v34, v13, v31, vcc
	v_pk_mul_f32 v[36:37], v[6:7], v[34:35] op_sel_hi:[1,0]
	v_pk_mul_f32 v[38:39], v[8:9], v[34:35] op_sel_hi:[1,0]
	v_pk_mul_f32 v[40:41], v[2:3], v[34:35] op_sel_hi:[1,0]
	v_pk_mul_f32 v[34:35], v[4:5], v[34:35] op_sel_hi:[1,0]
	v_pk_mul_f32 v[22:23], v[36:37], v[22:23]
	v_pk_mul_f32 v[20:21], v[38:39], v[20:21]
	v_pk_mul_f32 v[18:19], v[40:41], v[18:19]
	v_pk_mul_f32 v[34:35], v[34:35], v[16:17]
	v_cvt_pk_bf16_f32 v16, v22, v23
	v_cvt_pk_bf16_f32 v17, v20, v21
	v_cvt_pk_bf16_f32 v18, v18, v19
	v_cvt_pk_bf16_f32 v19, v34, v35
	v_mov_b32_e32 v13, v1
	ds_write_b128 v32, v[16:19]
	s_and_saveexec_b64 s[4:5], s[6:7]
	s_cbranch_execz .LBB0_398
	v_add_u32_e32 v12, s20, v30
	v_mov_b64_e32 v[10:11], s[10:11]
	v_mad_i64_i32 v[10:11], s[6:7], v12, s79, v[10:11]
	s_lshl_b32 s40, s42, 1
	v_lshl_add_u64 v[10:11], v[10:11], 0, s[40:41]
	v_lshl_add_u64 v[10:11], v[10:11], 0, v[160:161]
	s_waitcnt vmcnt(0)
	v_mov_b64_e32 v[10:11], v[188:189]
	v_mov_b64_e32 v[12:13], v[190:191]
.LBB0_398:
	s_or_b64 exec, exec, s[4:5]
	s_waitcnt vmcnt(0)
	v_lshlrev_b32_e32 v32, 16, v10
	v_and_b32_e32 v33, 0xffff0000, v10
	v_lshlrev_b32_e32 v22, 16, v11
	v_and_b32_e32 v23, 0xffff0000, v11
	v_pk_mul_f32 v[10:11], v[32:33], v[32:33]
	v_pk_mul_f32 v[30:31], v[22:23], v[22:23]
	v_add_f32_e32 v10, v10, v11
	v_lshlrev_b32_e32 v20, 16, v12
	v_and_b32_e32 v21, 0xffff0000, v12
	v_add_f32_e32 v10, v30, v10
	v_lshlrev_b32_e32 v16, 16, v13
	v_and_b32_e32 v17, 0xffff0000, v13
	v_pk_mul_f32 v[12:13], v[20:21], v[20:21]
	v_add_f32_e32 v10, v31, v10
	v_add_f32_e32 v10, v12, v10
	v_pk_mul_f32 v[18:19], v[16:17], v[16:17]
	v_add_f32_e32 v10, v13, v10
	v_add_f32_e32 v10, v18, v10
	v_add_f32_e32 v10, v19, v10
	s_waitcnt lgkmcnt(0)
	s_nop 1
	v_add_f32_dpp v10, v10, v10 quad_perm:[1,0,3,2] row_mask:0xf bank_mask:0xf
	s_waitcnt lgkmcnt(0)
	s_nop 1
	v_add_f32_dpp v10, v10, v10 quad_perm:[2,3,0,1] row_mask:0xf bank_mask:0xf
	s_waitcnt lgkmcnt(0)
	s_nop 1
	v_add_f32_dpp v10, v10, v10 row_half_mirror row_mask:0xf bank_mask:0xf
	v_fmamk_f32 v10, v10, 0x3c800000, v166
	v_mul_f32_e32 v11, 0x4b800000, v10
	v_cmp_gt_f32_e32 vcc, s78, v10
	s_nop 1
	v_cndmask_b32_e32 v10, v10, v11, vcc
	v_rsq_f32_e32 v10, v10
	s_nop 0
	v_mul_f32_e32 v11, 0x45800000, v10
	v_cndmask_b32_e32 v10, v10, v11, vcc
	v_pk_mul_f32 v[12:13], v[6:7], v[10:11] op_sel_hi:[1,0]
	v_pk_mul_f32 v[18:19], v[8:9], v[10:11] op_sel_hi:[1,0]
	v_pk_mul_f32 v[30:31], v[2:3], v[10:11] op_sel_hi:[1,0]
	v_pk_mul_f32 v[10:11], v[4:5], v[10:11] op_sel_hi:[1,0]
	v_pk_mul_f32 v[12:13], v[12:13], v[32:33]
	v_pk_mul_f32 v[18:19], v[18:19], v[22:23]
	v_pk_mul_f32 v[20:21], v[30:31], v[20:21]
	v_pk_mul_f32 v[16:17], v[10:11], v[16:17]
	v_cvt_pk_bf16_f32 v10, v12, v13
	v_cvt_pk_bf16_f32 v11, v18, v19
	v_cvt_pk_bf16_f32 v12, v20, v21
	v_cvt_pk_bf16_f32 v13, v16, v17
	v_mad_u64_u32 v[16:17], s[4:5], v29, s80, v[14:15]
	ds_write_b128 v16, v[10:13]
	v_add_u32_e32 v16, 0x400, v15
	v_ashrrev_i32_e32 v17, 3, v16
	v_add_u32_e32 v18, s1, v17
	v_cmp_lt_i32_e32 vcc, -1, v18
	v_cmp_gt_i32_e64 s[4:5], s0, v18
	v_mov_b64_e32 v[12:13], v[2:3]
	s_and_b64 s[6:7], vcc, s[4:5]
	v_mov_b64_e32 v[10:11], v[0:1]
	v_mov_b32_e32 v12, v1
	v_mov_b32_e32 v13, v1
	s_and_saveexec_b64 s[4:5], s[6:7]
	s_cbranch_execz .LBB0_400
	v_add_u32_e32 v12, s20, v18
	v_mov_b64_e32 v[10:11], s[10:11]
	v_mad_i64_i32 v[10:11], s[6:7], v12, s79, v[10:11]
	s_lshl_b32 s40, s42, 1
	v_lshl_add_u64 v[10:11], v[10:11], 0, s[40:41]
	v_lshl_add_u64 v[10:11], v[10:11], 0, v[160:161]
	s_waitcnt vmcnt(0)
	v_mov_b64_e32 v[10:11], v[192:193]
	v_mov_b64_e32 v[12:13], v[194:195]
.LBB0_400:
	s_or_b64 exec, exec, s[4:5]
	s_waitcnt vmcnt(0)
	v_lshlrev_b32_e32 v34, 16, v10
	v_and_b32_e32 v35, 0xffff0000, v10
	v_lshlrev_b32_e32 v30, 16, v11
	v_and_b32_e32 v31, 0xffff0000, v11
	v_pk_mul_f32 v[10:11], v[34:35], v[34:35]
	v_pk_mul_f32 v[32:33], v[30:31], v[30:31]
	v_add_f32_e32 v10, v10, v11
	v_lshlrev_b32_e32 v22, 16, v12
	v_and_b32_e32 v23, 0xffff0000, v12
	v_add_f32_e32 v10, v32, v10
	v_lshlrev_b32_e32 v18, 16, v13
	v_and_b32_e32 v19, 0xffff0000, v13
	v_pk_mul_f32 v[12:13], v[22:23], v[22:23]
	v_add_f32_e32 v10, v33, v10
	v_add_f32_e32 v10, v12, v10
	v_pk_mul_f32 v[20:21], v[18:19], v[18:19]
	v_add_f32_e32 v10, v13, v10
	v_add_f32_e32 v10, v20, v10
	v_add_f32_e32 v10, v21, v10
	s_waitcnt lgkmcnt(0)
	s_nop 1
	v_add_f32_dpp v10, v10, v10 quad_perm:[1,0,3,2] row_mask:0xf bank_mask:0xf
	s_waitcnt lgkmcnt(0)
	s_nop 1
	v_add_f32_dpp v10, v10, v10 quad_perm:[2,3,0,1] row_mask:0xf bank_mask:0xf
	s_waitcnt lgkmcnt(0)
	s_nop 1
	v_add_f32_dpp v10, v10, v10 row_half_mirror row_mask:0xf bank_mask:0xf
	v_fmamk_f32 v10, v10, 0x3c800000, v166
	v_mul_f32_e32 v11, 0x4b800000, v10
	v_cmp_gt_f32_e32 vcc, s78, v10
	s_nop 1
	v_cndmask_b32_e32 v10, v10, v11, vcc
	v_rsq_f32_e32 v10, v10
	s_nop 0
	v_mul_f32_e32 v11, 0x45800000, v10
	v_cndmask_b32_e32 v10, v10, v11, vcc
	v_pk_mul_f32 v[12:13], v[6:7], v[10:11] op_sel_hi:[1,0]
	v_pk_mul_f32 v[20:21], v[8:9], v[10:11] op_sel_hi:[1,0]
	v_pk_mul_f32 v[32:33], v[2:3], v[10:11] op_sel_hi:[1,0]
	v_pk_mul_f32 v[10:11], v[4:5], v[10:11] op_sel_hi:[1,0]
	v_pk_mul_f32 v[12:13], v[12:13], v[34:35]
	v_pk_mul_f32 v[20:21], v[20:21], v[30:31]
	v_pk_mul_f32 v[22:23], v[32:33], v[22:23]
	v_pk_mul_f32 v[18:19], v[10:11], v[18:19]
	v_cvt_pk_bf16_f32 v10, v12, v13
	v_cvt_pk_bf16_f32 v11, v20, v21
	v_cvt_pk_bf16_f32 v12, v22, v23
	v_cvt_pk_bf16_f32 v13, v18, v19
	v_mad_u64_u32 v[18:19], s[4:5], v17, s80, v[14:15]
	v_add_u32_e32 v17, 0x600, v15
	ds_write_b128 v18, v[10:13]
	v_ashrrev_i32_e32 v18, 3, v17
	v_add_u32_e32 v19, s1, v18
	v_cmp_lt_i32_e32 vcc, -1, v19
	v_cmp_gt_i32_e64 s[4:5], s0, v19
	v_mov_b64_e32 v[12:13], v[2:3]
	s_and_b64 s[6:7], vcc, s[4:5]
	v_mov_b64_e32 v[10:11], v[0:1]
	v_mov_b32_e32 v12, v1
	v_mov_b32_e32 v13, v1
	s_and_saveexec_b64 s[4:5], s[6:7]
	s_cbranch_execz .LBB0_402
	v_add_u32_e32 v12, s20, v19
	v_mov_b64_e32 v[10:11], s[10:11]
	v_mad_i64_i32 v[10:11], s[6:7], v12, s79, v[10:11]
	s_lshl_b32 s40, s42, 1
	v_lshl_add_u64 v[10:11], v[10:11], 0, s[40:41]
	v_lshl_add_u64 v[10:11], v[10:11], 0, v[160:161]
	s_waitcnt vmcnt(0)
	v_mov_b64_e32 v[10:11], v[196:197]
	v_mov_b64_e32 v[12:13], v[198:199]
.LBB0_402:
	s_or_b64 exec, exec, s[4:5]
	s_waitcnt vmcnt(0)
	v_lshlrev_b32_e32 v36, 16, v10
	v_and_b32_e32 v37, 0xffff0000, v10
	v_lshlrev_b32_e32 v32, 16, v11
	v_and_b32_e32 v33, 0xffff0000, v11
	v_pk_mul_f32 v[10:11], v[36:37], v[36:37]
	v_pk_mul_f32 v[34:35], v[32:33], v[32:33]
	v_add_f32_e32 v10, v10, v11
	v_lshlrev_b32_e32 v30, 16, v12
	v_and_b32_e32 v31, 0xffff0000, v12
	v_add_f32_e32 v10, v34, v10
	v_lshlrev_b32_e32 v20, 16, v13
	v_and_b32_e32 v21, 0xffff0000, v13
	v_pk_mul_f32 v[12:13], v[30:31], v[30:31]
	v_add_f32_e32 v10, v35, v10
	v_add_f32_e32 v10, v12, v10
	v_pk_mul_f32 v[22:23], v[20:21], v[20:21]
	v_add_f32_e32 v10, v13, v10
	v_add_f32_e32 v10, v22, v10
	v_add_f32_e32 v10, v23, v10
	v_mad_u64_u32 v[18:19], s[4:5], v18, s80, v[14:15]
	s_waitcnt lgkmcnt(0)
	s_nop 1
	v_add_f32_dpp v10, v10, v10 quad_perm:[1,0,3,2] row_mask:0xf bank_mask:0xf
	s_waitcnt lgkmcnt(0)
	s_nop 1
	v_add_f32_dpp v10, v10, v10 quad_perm:[2,3,0,1] row_mask:0xf bank_mask:0xf
	s_waitcnt lgkmcnt(0)
	s_nop 1
	v_add_f32_dpp v10, v10, v10 row_half_mirror row_mask:0xf bank_mask:0xf
	v_fmamk_f32 v10, v10, 0x3c800000, v166
	v_mul_f32_e32 v11, 0x4b800000, v10
	v_cmp_gt_f32_e32 vcc, s78, v10
	s_nop 1
	v_cndmask_b32_e32 v10, v10, v11, vcc
	v_rsq_f32_e32 v10, v10
	s_nop 0
	v_mul_f32_e32 v11, 0x45800000, v10
	v_cndmask_b32_e32 v10, v10, v11, vcc
	v_pk_mul_f32 v[12:13], v[6:7], v[10:11] op_sel_hi:[1,0]
	v_pk_mul_f32 v[22:23], v[8:9], v[10:11] op_sel_hi:[1,0]
	v_pk_mul_f32 v[34:35], v[2:3], v[10:11] op_sel_hi:[1,0]
	v_pk_mul_f32 v[10:11], v[4:5], v[10:11] op_sel_hi:[1,0]
	v_pk_mul_f32 v[12:13], v[12:13], v[36:37]
	v_pk_mul_f32 v[22:23], v[22:23], v[32:33]
	v_pk_mul_f32 v[30:31], v[34:35], v[30:31]
	v_pk_mul_f32 v[20:21], v[10:11], v[20:21]
	v_cvt_pk_bf16_f32 v10, v12, v13
	v_cvt_pk_bf16_f32 v11, v22, v23
	v_cvt_pk_bf16_f32 v12, v30, v31
	v_cvt_pk_bf16_f32 v13, v20, v21
	ds_write_b128 v18, v[10:13]
	v_add_u32_e32 v18, 0x800, v15
	v_ashrrev_i32_e32 v19, 3, v18
	v_add_u32_e32 v20, s1, v19
	v_cmp_lt_i32_e32 vcc, -1, v20
	v_cmp_gt_i32_e64 s[4:5], s0, v20
	v_mov_b64_e32 v[12:13], v[2:3]
	s_and_b64 s[6:7], vcc, s[4:5]
	v_mov_b64_e32 v[10:11], v[0:1]
	v_mov_b32_e32 v12, v1
	v_mov_b32_e32 v13, v1
	s_and_saveexec_b64 s[4:5], s[6:7]
	s_cbranch_execz .LBB0_404
	v_add_u32_e32 v12, s20, v20
	v_mov_b64_e32 v[10:11], s[10:11]
	v_mad_i64_i32 v[10:11], s[6:7], v12, s79, v[10:11]
	s_lshl_b32 s40, s42, 1
	v_lshl_add_u64 v[10:11], v[10:11], 0, s[40:41]
	v_lshl_add_u64 v[10:11], v[10:11], 0, v[160:161]
	s_waitcnt vmcnt(0)
	v_mov_b64_e32 v[10:11], v[200:201]
	v_mov_b64_e32 v[12:13], v[202:203]
.LBB0_404:
	s_or_b64 exec, exec, s[4:5]
	s_waitcnt vmcnt(0)
	v_lshlrev_b32_e32 v36, 16, v10
	v_and_b32_e32 v37, 0xffff0000, v10
	v_lshlrev_b32_e32 v32, 16, v11
	v_and_b32_e32 v33, 0xffff0000, v11
	v_pk_mul_f32 v[10:11], v[36:37], v[36:37]
	v_pk_mul_f32 v[34:35], v[32:33], v[32:33]
	v_add_f32_e32 v10, v10, v11
	v_lshlrev_b32_e32 v30, 16, v12
	v_and_b32_e32 v31, 0xffff0000, v12
	v_add_f32_e32 v10, v34, v10
	v_lshlrev_b32_e32 v20, 16, v13
	v_and_b32_e32 v21, 0xffff0000, v13
	v_pk_mul_f32 v[12:13], v[30:31], v[30:31]
	v_add_f32_e32 v10, v35, v10
	v_add_f32_e32 v10, v12, v10
	v_pk_mul_f32 v[22:23], v[20:21], v[20:21]
	v_add_f32_e32 v10, v13, v10
	v_add_f32_e32 v10, v22, v10
	v_add_f32_e32 v10, v23, v10
	s_waitcnt lgkmcnt(0)
	s_nop 1
	v_add_f32_dpp v10, v10, v10 quad_perm:[1,0,3,2] row_mask:0xf bank_mask:0xf
	s_waitcnt lgkmcnt(0)
	s_nop 1
	v_add_f32_dpp v10, v10, v10 quad_perm:[2,3,0,1] row_mask:0xf bank_mask:0xf
	s_waitcnt lgkmcnt(0)
	s_nop 1
	v_add_f32_dpp v10, v10, v10 row_half_mirror row_mask:0xf bank_mask:0xf
	v_fmamk_f32 v10, v10, 0x3c800000, v166
	v_mul_f32_e32 v11, 0x4b800000, v10
	v_cmp_gt_f32_e32 vcc, s78, v10
	s_nop 1
	v_cndmask_b32_e32 v10, v10, v11, vcc
	v_rsq_f32_e32 v10, v10
	s_nop 0
	v_mul_f32_e32 v11, 0x45800000, v10
	v_cndmask_b32_e32 v10, v10, v11, vcc
	v_pk_mul_f32 v[12:13], v[6:7], v[10:11] op_sel_hi:[1,0]
	v_pk_mul_f32 v[22:23], v[8:9], v[10:11] op_sel_hi:[1,0]
	v_pk_mul_f32 v[34:35], v[2:3], v[10:11] op_sel_hi:[1,0]
	v_pk_mul_f32 v[10:11], v[4:5], v[10:11] op_sel_hi:[1,0]
	v_pk_mul_f32 v[12:13], v[12:13], v[36:37]
	v_pk_mul_f32 v[22:23], v[22:23], v[32:33]
	v_pk_mul_f32 v[30:31], v[34:35], v[30:31]
	v_pk_mul_f32 v[20:21], v[10:11], v[20:21]
	v_cvt_pk_bf16_f32 v10, v12, v13
	v_cvt_pk_bf16_f32 v11, v22, v23
	v_cvt_pk_bf16_f32 v12, v30, v31
	v_cvt_pk_bf16_f32 v13, v20, v21
	v_mad_u64_u32 v[20:21], s[4:5], v19, s80, v[14:15]
	v_add_u32_e32 v19, 0xa00, v15
	ds_write_b128 v20, v[10:13]
	v_ashrrev_i32_e32 v20, 3, v19
	v_add_u32_e32 v21, s1, v20
	v_cmp_lt_i32_e32 vcc, -1, v21
	v_cmp_gt_i32_e64 s[4:5], s0, v21
	v_mov_b64_e32 v[12:13], v[2:3]
	s_and_b64 s[6:7], vcc, s[4:5]
	v_mov_b64_e32 v[10:11], v[0:1]
	v_mov_b32_e32 v12, v1
	v_mov_b32_e32 v13, v1
	s_and_saveexec_b64 s[4:5], s[6:7]
	s_cbranch_execz .LBB0_406
	v_add_u32_e32 v12, s20, v21
	v_mov_b64_e32 v[10:11], s[10:11]
	v_mad_i64_i32 v[10:11], s[6:7], v12, s79, v[10:11]
	s_lshl_b32 s40, s42, 1
	v_lshl_add_u64 v[10:11], v[10:11], 0, s[40:41]
	v_lshl_add_u64 v[10:11], v[10:11], 0, v[160:161]
	s_waitcnt vmcnt(0)
	v_mov_b64_e32 v[10:11], v[204:205]
	v_mov_b64_e32 v[12:13], v[206:207]
.LBB0_406:
	s_or_b64 exec, exec, s[4:5]
	s_waitcnt vmcnt(0)
	v_lshlrev_b32_e32 v38, 16, v10
	v_and_b32_e32 v39, 0xffff0000, v10
	v_lshlrev_b32_e32 v34, 16, v11
	v_and_b32_e32 v35, 0xffff0000, v11
	v_pk_mul_f32 v[10:11], v[38:39], v[38:39]
	v_pk_mul_f32 v[36:37], v[34:35], v[34:35]
	v_add_f32_e32 v10, v10, v11
	v_lshlrev_b32_e32 v32, 16, v12
	v_and_b32_e32 v33, 0xffff0000, v12
	v_add_f32_e32 v10, v36, v10
	v_lshlrev_b32_e32 v22, 16, v13
	v_and_b32_e32 v23, 0xffff0000, v13
	v_pk_mul_f32 v[12:13], v[32:33], v[32:33]
	v_add_f32_e32 v10, v37, v10
	v_add_f32_e32 v10, v12, v10
	v_pk_mul_f32 v[30:31], v[22:23], v[22:23]
	v_add_f32_e32 v10, v13, v10
	v_add_f32_e32 v10, v30, v10
	v_add_f32_e32 v10, v31, v10
	s_waitcnt lgkmcnt(0)
	s_nop 1
	v_add_f32_dpp v10, v10, v10 quad_perm:[1,0,3,2] row_mask:0xf bank_mask:0xf
	s_waitcnt lgkmcnt(0)
	s_nop 1
	v_add_f32_dpp v10, v10, v10 quad_perm:[2,3,0,1] row_mask:0xf bank_mask:0xf
	s_waitcnt lgkmcnt(0)
	s_nop 1
	v_add_f32_dpp v10, v10, v10 row_half_mirror row_mask:0xf bank_mask:0xf
	v_fmamk_f32 v10, v10, 0x3c800000, v166
	v_mul_f32_e32 v11, 0x4b800000, v10
	v_cmp_gt_f32_e32 vcc, s78, v10
	s_nop 1
	v_cndmask_b32_e32 v10, v10, v11, vcc
	v_rsq_f32_e32 v10, v10
	s_nop 0
	v_mul_f32_e32 v11, 0x45800000, v10
	v_cndmask_b32_e32 v10, v10, v11, vcc
	v_pk_mul_f32 v[2:3], v[2:3], v[10:11] op_sel_hi:[1,0]
	v_pk_mul_f32 v[6:7], v[6:7], v[10:11] op_sel_hi:[1,0]
	v_pk_mul_f32 v[8:9], v[8:9], v[10:11] op_sel_hi:[1,0]
	v_pk_mul_f32 v[12:13], v[2:3], v[32:33]
	v_pk_mul_f32 v[2:3], v[4:5], v[10:11] op_sel_hi:[1,0]
	v_pk_mul_f32 v[6:7], v[6:7], v[38:39]
	v_pk_mul_f32 v[8:9], v[8:9], v[34:35]
	v_pk_mul_f32 v[10:11], v[2:3], v[22:23]
	v_cvt_pk_bf16_f32 v2, v6, v7
	v_cvt_pk_bf16_f32 v3, v8, v9
	v_cvt_pk_bf16_f32 v4, v12, v13
	v_cvt_pk_bf16_f32 v5, v10, v11
	v_mad_u64_u32 v[6:7], s[4:5], v20, s80, v[14:15]
	ds_write_b128 v6, v[2:5]
	v_mul_hi_i32 v2, v15, s84
	v_lshrrev_b32_e32 v3, 31, v2
	v_ashrrev_i32_e32 v2, 6, v2
	v_add_u32_e32 v6, v2, v3
	v_mul_i32_i24_e32 v2, 0x180, v6
	v_sub_u32_e32 v7, v15, v2
	v_add_u32_e32 v8, s1, v7
	v_mov_b64_e32 v[4:5], v[2:3]
	v_cmp_lt_i32_e32 vcc, -1, v8
	v_cmp_gt_i32_e64 s[4:5], s0, v8
	v_mov_b64_e32 v[2:3], v[0:1]
	s_and_b64 s[6:7], vcc, s[4:5]
	v_mov_b32_e32 v3, v1
	v_mov_b32_e32 v4, v1
	v_mov_b32_e32 v5, v1
	s_and_saveexec_b64 s[4:5], s[6:7]
	s_cbranch_execz .LBB0_408
	v_add_u32_e32 v4, s20, v8
	v_mov_b64_e32 v[2:3], s[10:11]
	v_mad_i64_i32 v[2:3], s[6:7], v4, s79, v[2:3]
	s_lshl_b32 s40, s42, 1
	v_lshlrev_b32_e32 v4, 3, v6
	v_lshl_add_u64 v[2:3], v[2:3], 0, s[40:41]
	v_ashrrev_i32_e32 v5, 31, v4
	v_lshl_add_u64 v[2:3], v[4:5], 1, v[2:3]
	s_waitcnt vmcnt(0)
	v_mov_b64_e32 v[2:3], v[208:209]
	v_mov_b64_e32 v[4:5], v[210:211]

.LBB0_588:
	v_mov_b32_e32 v97, v167
	s_load_dwordx2 s[14:15], s[8:9], 0x98
	s_load_dwordx4 s[4:7], s[8:9], 0xd0
	v_ashrrev_i32_e32 v96, 3, v97
	v_and_b32_e32 v102, -8, v96
	v_add_u32_e32 v0, s10, v102
	v_ashrrev_i32_e32 v1, 31, v0
	v_and_b32_e32 v4, 63, v97
	v_lshlrev_b64 v[2:3], 11, v[0:1]
	v_lshlrev_b32_e32 v160, 3, v4
	s_waitcnt lgkmcnt(0)
	v_lshl_add_u64 v[2:3], s[4:5], 0, v[2:3]
	v_lshlrev_b32_e32 v48, 4, v4
	v_mov_b32_e32 v49, v161
	v_lshl_add_u64 v[94:95], v[2:3], 0, v[48:49]
	v_lshl_add_u64 v[90:91], v[2:3], 0, v[160:161]
	v_add_u32_e32 v2, 1, v0
	v_ashrrev_i32_e32 v3, 31, v2
	v_lshlrev_b64 v[2:3], 11, v[2:3]
	v_lshl_add_u64 v[2:3], s[4:5], 0, v[2:3]
	v_lshl_add_u64 v[88:89], v[2:3], 0, v[48:49]
	v_lshl_add_u64 v[84:85], v[2:3], 0, v[160:161]
	v_add_u32_e32 v2, 2, v0
	v_ashrrev_i32_e32 v3, 31, v2
	v_lshlrev_b64 v[2:3], 11, v[2:3]
	v_lshl_add_u64 v[2:3], s[4:5], 0, v[2:3]
	v_lshl_add_u64 v[82:83], v[2:3], 0, v[48:49]
	v_lshl_add_u64 v[78:79], v[2:3], 0, v[160:161]
	v_add_u32_e32 v2, 3, v0
	v_ashrrev_i32_e32 v3, 31, v2
	v_lshlrev_b64 v[2:3], 11, v[2:3]
	v_lshl_add_u64 v[2:3], s[4:5], 0, v[2:3]
	v_lshl_add_u64 v[76:77], v[2:3], 0, v[48:49]
	v_lshl_add_u64 v[72:73], v[2:3], 0, v[160:161]
	v_add_u32_e32 v2, 4, v0
	v_ashrrev_i32_e32 v3, 31, v2
	v_lshlrev_b64 v[2:3], 11, v[2:3]
	v_lshl_add_u64 v[2:3], s[4:5], 0, v[2:3]
	v_lshl_add_u64 v[70:71], v[2:3], 0, v[48:49]
	v_lshl_add_u64 v[66:67], v[2:3], 0, v[160:161]
	v_add_u32_e32 v2, 5, v0
	v_ashrrev_i32_e32 v3, 31, v2
	v_lshlrev_b64 v[2:3], 11, v[2:3]
	v_lshl_add_u64 v[2:3], s[4:5], 0, v[2:3]
	v_lshl_add_u64 v[64:65], v[2:3], 0, v[48:49]
	v_lshl_add_u64 v[60:61], v[2:3], 0, v[160:161]
	v_add_u32_e32 v2, 6, v0
	v_add_u32_e32 v0, 7, v0
	v_ashrrev_i32_e32 v3, 31, v2
	v_ashrrev_i32_e32 v1, 31, v0
	v_lshlrev_b64 v[2:3], 11, v[2:3]
	v_lshlrev_b64 v[0:1], 11, v[0:1]
	v_lshl_add_u64 v[2:3], s[4:5], 0, v[2:3]
	v_lshl_add_u64 v[0:1], s[4:5], 0, v[0:1]
	v_lshl_add_u64 v[58:59], v[2:3], 0, v[48:49]
	v_lshl_add_u64 v[54:55], v[2:3], 0, v[160:161]
	v_lshl_add_u64 v[2:3], v[0:1], 0, v[48:49]
	v_lshl_add_u64 v[0:1], v[0:1], 0, v[160:161]
	s_add_u32 s0, s14, s12
	global_load_dwordx4 v[16:19], v[2:3], off
	global_load_dwordx2 v[50:51], v[0:1], off offset:1024
	s_addc_u32 s1, s15, s13
	v_lshlrev_b32_e32 v0, 5, v4
	s_ashr_i32 s11, s10, 31
	global_load_dwordx4 v[44:47], v[94:95], off
	global_load_dwordx2 v[92:93], v[90:91], off offset:1024
	global_load_dwordx4 v[40:43], v[88:89], off
	global_load_dwordx2 v[86:87], v[84:85], off offset:1024
	global_load_dwordx4 v[36:39], v[82:83], off
	global_load_dwordx2 v[80:81], v[78:79], off offset:1024
	global_load_dwordx4 v[32:35], v[76:77], off
	global_load_dwordx2 v[74:75], v[72:73], off offset:1024
	global_load_dwordx4 v[28:31], v[70:71], off
	global_load_dwordx2 v[68:69], v[66:67], off offset:1024
	global_load_dwordx4 v[24:27], v[64:65], off
	global_load_dwordx2 v[62:63], v[60:61], off offset:1024
	global_load_dwordx4 v[20:23], v[58:59], off
	global_load_dwordx2 v[56:57], v[54:55], off offset:1024
	global_load_dwordx4 v[8:11], v0, s[0:1] offset:16
	global_load_dwordx4 v[12:15], v0, s[0:1]
	global_load_dwordx4 v[4:7], v48, s[0:1] offset:2048
	s_nop 0
	global_load_dwordx4 v[0:3], v48, s[0:1] offset:3072
	s_lshl_b64 s[0:1], s[10:11], 1
	v_lshlrev_b32_e32 v52, 3, v97
	s_add_u32 s6, s6, s0
	v_and_b32_e32 v103, 56, v52
	s_addc_u32 s7, s7, s1
	v_lshlrev_b32_e32 v52, 1, v103
	v_mov_b32_e32 v53, v161
	v_lshl_add_u64 v[52:53], s[6:7], 0, v[52:53]
	s_mov_b64 s[0:1], 0x18600000
	v_lshl_add_u64 v[52:53], v[52:53], 0, s[0:1]
	v_add_u32_e32 v104, 0x200, v97
	v_mad_i64_i32 v[98:99], s[0:1], v96, s76, v[52:53]
	v_ashrrev_i32_e32 v116, 3, v104
	global_load_dwordx4 v[98:101], v[98:99], off
	v_mad_i64_i32 v[104:105], s[0:1], v116, s76, v[52:53]
	global_load_dwordx4 v[104:107], v[104:105], off
	v_add_u32_e32 v108, 0x400, v97
	v_ashrrev_i32_e32 v117, 3, v108
	v_add_u32_e32 v97, 0x600, v97
	v_mad_i64_i32 v[108:109], s[0:1], v117, s76, v[52:53]
	v_ashrrev_i32_e32 v97, 3, v97
	global_load_dwordx4 v[108:111], v[108:109], off
	v_mad_i64_i32 v[52:53], s[0:1], v97, s76, v[52:53]
	global_load_dwordx4 v[112:115], v[52:53], off
	v_lshlrev_b32_e32 v120, 2, v96
	v_mul_u32_u24_e32 v103, 0x404, v103
	v_add3_u32 v120, 0, v120, v103
	v_lshlrev_b32_e32 v97, 2, v97
	v_add3_u32 v97, 0, v97, v103
	s_add_i32 s16, s16, s17
	s_waitcnt vmcnt(0)
	v_lshlrev_b32_e32 v52, 16, v98
	v_lshlrev_b32_e32 v118, 16, v100
	v_and_b32_e32 v100, 0xffff0000, v100
	v_lshlrev_b32_e32 v119, 16, v101
	v_and_b32_e32 v101, 0xffff0000, v101
	v_and_b32_e32 v53, 0xffff0000, v98
	v_lshlrev_b32_e32 v98, 16, v99
	v_and_b32_e32 v99, 0xffff0000, v99
	ds_write_b32 v120, v52
	ds_write_b32 v120, v53 offset:1028
	ds_write_b32 v120, v98 offset:2056
	ds_write_b32 v120, v99 offset:3084
	ds_write_b32 v120, v118 offset:4112
	ds_write_b32 v120, v100 offset:5140
	ds_write_b32 v120, v119 offset:6168
	ds_write_b32 v120, v101 offset:7196
	v_lshlrev_b32_e32 v100, 16, v106
	v_and_b32_e32 v101, 0xffff0000, v106
	v_lshlrev_b32_e32 v106, 2, v116
	v_lshlrev_b32_e32 v52, 16, v104
	v_add3_u32 v106, 0, v106, v103
	v_and_b32_e32 v53, 0xffff0000, v104
	v_lshlrev_b32_e32 v98, 16, v105
	v_and_b32_e32 v99, 0xffff0000, v105
	v_lshlrev_b32_e32 v104, 16, v107
	v_and_b32_e32 v105, 0xffff0000, v107
	ds_write_b32 v106, v52
	ds_write_b32 v106, v53 offset:1028
	ds_write_b32 v106, v98 offset:2056
	ds_write_b32 v106, v99 offset:3084
	ds_write_b32 v106, v100 offset:4112
	ds_write_b32 v106, v101 offset:5140
	ds_write_b32 v106, v104 offset:6168
	ds_write_b32 v106, v105 offset:7196
	v_lshlrev_b32_e32 v106, 2, v117
	v_lshlrev_b32_e32 v52, 16, v108
	v_lshlrev_b32_e32 v100, 16, v110
	v_and_b32_e32 v101, 0xffff0000, v110
	v_lshlrev_b32_e32 v104, 16, v111
	v_and_b32_e32 v105, 0xffff0000, v111
	v_add3_u32 v106, 0, v106, v103
	v_and_b32_e32 v53, 0xffff0000, v108
	v_lshlrev_b32_e32 v98, 16, v109
	v_and_b32_e32 v99, 0xffff0000, v109
	ds_write_b32 v106, v52
	ds_write_b32 v106, v53 offset:1028
	ds_write_b32 v106, v98 offset:2056
	ds_write_b32 v106, v99 offset:3084
	ds_write_b32 v106, v100 offset:4112
	ds_write_b32 v106, v101 offset:5140
	ds_write_b32 v106, v104 offset:6168
	ds_write_b32 v106, v105 offset:7196
	v_lshlrev_b32_e32 v100, 16, v114
	v_and_b32_e32 v101, 0xffff0000, v114
	v_lshlrev_b32_e32 v104, 16, v115
	v_and_b32_e32 v105, 0xffff0000, v115
	v_lshlrev_b32_e32 v114, 16, v44
	v_and_b32_e32 v115, 0xffff0000, v44
	v_lshlrev_b32_e32 v110, 16, v45
	v_and_b32_e32 v111, 0xffff0000, v45
	v_pk_mul_f32 v[44:45], v[114:115], v[114:115]
	v_lshlrev_b32_e32 v52, 16, v112
	v_and_b32_e32 v53, 0xffff0000, v112
	v_lshlrev_b32_e32 v98, 16, v113
	v_and_b32_e32 v99, 0xffff0000, v113
	v_pk_mul_f32 v[112:113], v[110:111], v[110:111]
	v_add_f32_e32 v44, v44, v45
	v_lshlrev_b32_e32 v108, 16, v46
	v_and_b32_e32 v109, 0xffff0000, v46
	v_add_f32_e32 v44, v112, v44
	ds_write_b32 v97, v52
	ds_write_b32 v97, v53 offset:1028
	ds_write_b32 v97, v98 offset:2056
	ds_write_b32 v97, v99 offset:3084
	ds_write_b32 v97, v100 offset:4112
	ds_write_b32 v97, v101 offset:5140
	ds_write_b32 v97, v104 offset:6168
	ds_write_b32 v97, v105 offset:7196
	v_and_b32_e32 v52, 64, v217
	v_lshlrev_b32_e32 v104, 16, v47
	v_and_b32_e32 v105, 0xffff0000, v47
	v_pk_mul_f32 v[46:47], v[108:109], v[108:109]
	v_add_f32_e32 v44, v113, v44
	v_add_u32_e32 v52, 64, v52
	v_xor_b32_e32 v53, 1, v217
	v_add_f32_e32 v44, v46, v44
	v_cmp_lt_i32_e32 vcc, v53, v52
	v_pk_mul_f32 v[106:107], v[104:105], v[104:105]
	v_add_f32_e32 v44, v47, v44
	v_cndmask_b32_e32 v53, v217, v53, vcc
	v_add_f32_e32 v44, v106, v44
	v_lshlrev_b32_e32 v53, 2, v53
	v_add_f32_e32 v44, v107, v44
	v_xor_b32_e32 v97, 2, v217
	v_cmp_lt_i32_e32 vcc, v97, v52
	v_xor_b32_e32 v98, 4, v217
	v_xor_b32_e32 v99, 8, v217
	v_cndmask_b32_e32 v97, v217, v97, vcc
	v_lshlrev_b32_e32 v97, 2, v97
	s_waitcnt lgkmcnt(0)
	s_nop 1
	v_add_f32_dpp v44, v44, v44 quad_perm:[1,0,3,2] row_mask:0xf bank_mask:0xf
	v_cmp_lt_i32_e32 vcc, v98, v52
	v_xor_b32_e32 v100, 16, v217
	v_xor_b32_e32 v101, 32, v217
	v_cndmask_b32_e32 v98, v217, v98, vcc
	v_lshlrev_b32_e32 v98, 2, v98
	s_waitcnt lgkmcnt(0)
	s_nop 1
	v_add_f32_dpp v44, v44, v44 quad_perm:[2,3,0,1] row_mask:0xf bank_mask:0xf
	v_cmp_lt_i32_e32 vcc, v99, v52
	s_waitcnt lgkmcnt(0)
	s_barrier
	v_cndmask_b32_e32 v99, v217, v99, vcc
	v_lshlrev_b32_e32 v99, 2, v99
	s_nop 1
	v_add_f32_dpp v44, v44, v44 row_half_mirror row_mask:0xf bank_mask:0xf
	v_cmp_lt_i32_e32 vcc, v100, v52
	s_waitcnt lgkmcnt(0)
	s_nop 1
	v_add_f32_dpp v44, v44, v44 row_mirror row_mask:0xf bank_mask:0xf
	v_cndmask_b32_e32 v100, v217, v100, vcc
	v_lshlrev_b32_e32 v100, 2, v100
	ds_bpermute_b32 v45, v100, v44
	v_cmp_lt_i32_e32 vcc, v101, v52
	s_waitcnt lgkmcnt(0)
	v_add_f32_e32 v44, v44, v45
	v_cndmask_b32_e32 v52, v217, v101, vcc
	v_lshlrev_b32_e32 v101, 2, v52
	ds_bpermute_b32 v45, v101, v44
	v_add_u32_e32 v52, 0, v48
	s_waitcnt lgkmcnt(0)
	v_add_f32_e32 v44, v44, v45
	v_fmamk_f32 v44, v44, 0x3b000000, v166
	v_rsq_f32_e32 v44, v44
	s_nop 0
	v_pk_mul_f32 v[106:107], v[8:9], v[44:45] op_sel_hi:[1,0]
	v_pk_mul_f32 v[46:47], v[12:13], v[44:45] op_sel_hi:[1,0]
	v_pk_mul_f32 v[106:107], v[106:107], v[108:109]
	v_pk_mul_f32 v[108:109], v[14:15], v[44:45] op_sel_hi:[1,0]
	v_pk_mul_f32 v[44:45], v[10:11], v[44:45] op_sel_hi:[1,0]
	v_pk_mul_f32 v[46:47], v[46:47], v[114:115]
	v_pk_mul_f32 v[108:109], v[108:109], v[110:111]
	v_pk_mul_f32 v[104:105], v[44:45], v[104:105]
	v_cvt_pk_bf16_f32 v44, v46, v47
	v_cvt_pk_bf16_f32 v45, v108, v109
	v_cvt_pk_bf16_f32 v46, v106, v107
	v_cvt_pk_bf16_f32 v47, v104, v105
	global_store_dwordx4 v[94:95], v[44:47], off
	v_lshlrev_b32_e32 v94, 16, v92
	v_and_b32_e32 v95, 0xffff0000, v92
	v_lshlrev_b32_e32 v44, 16, v93
	v_and_b32_e32 v45, 0xffff0000, v93
	v_pk_mul_f32 v[92:93], v[94:95], v[94:95]
	v_pk_mul_f32 v[46:47], v[44:45], v[44:45]
	v_add_f32_e32 v92, v92, v93
	v_add_f32_e32 v46, v46, v92
	v_add_f32_e32 v46, v47, v46
	v_lshlrev_b32_e32 v104, 16, v40
	v_and_b32_e32 v105, 0xffff0000, v40
	s_waitcnt lgkmcnt(0)
	s_nop 1
	v_add_f32_dpp v46, v46, v46 quad_perm:[1,0,3,2] row_mask:0xf bank_mask:0xf
	s_waitcnt lgkmcnt(0)
	s_nop 1
	v_add_f32_dpp v46, v46, v46 quad_perm:[2,3,0,1] row_mask:0xf bank_mask:0xf
	s_waitcnt lgkmcnt(0)
	s_nop 1
	v_add_f32_dpp v46, v46, v46 row_half_mirror row_mask:0xf bank_mask:0xf
	s_waitcnt lgkmcnt(0)
	s_nop 1
	v_add_f32_dpp v46, v46, v46 row_mirror row_mask:0xf bank_mask:0xf
	ds_bpermute_b32 v47, v100, v46
	s_waitcnt lgkmcnt(0)
	v_add_f32_e32 v46, v46, v47
	ds_bpermute_b32 v47, v101, v46
	s_waitcnt lgkmcnt(0)
	v_add_f32_e32 v46, v46, v47
	v_fmamk_f32 v46, v46, 0x3b800000, v166
	v_rsq_f32_e32 v46, v46
	s_nop 0
	v_pk_mul_f32 v[92:93], v[46:47], v[94:95] op_sel_hi:[0,1]
	v_pk_mul_f32 v[44:45], v[46:47], v[44:45] op_sel_hi:[0,1]
	v_pk_mul_f32 v[92:93], v[4:5], v[92:93]
	v_pk_mul_f32 v[44:45], v[6:7], v[44:45]
	v_cvt_pk_bf16_f32 v92, v92, v93
	v_cvt_pk_bf16_f32 v93, v44, v45
	v_mad_u64_u32 v[44:45], s[0:1], v102, s86, v[52:53]
	global_store_dwordx2 v[90:91], v[92:93], off offset:1024
	ds_read_b128 v[92:95], v44
	s_waitcnt lgkmcnt(0)
	v_pk_mul_f32 v[102:103], v[92:93], v[92:93]
	v_pk_mul_f32 v[46:47], v[94:95], v[94:95]
	v_add_f32_e32 v45, v102, v103
	v_add_f32_e32 v45, v45, v46
	v_add_f32_e32 v45, v45, v47
	s_waitcnt lgkmcnt(0)
	s_nop 1
	v_add_f32_dpp v45, v45, v45 quad_perm:[1,0,3,2] row_mask:0xf bank_mask:0xf
	s_waitcnt lgkmcnt(0)
	s_nop 1
	v_add_f32_dpp v45, v45, v45 quad_perm:[2,3,0,1] row_mask:0xf bank_mask:0xf
	s_waitcnt lgkmcnt(0)
	s_nop 1
	v_add_f32_dpp v45, v45, v45 row_half_mirror row_mask:0xf bank_mask:0xf
	s_waitcnt lgkmcnt(0)
	s_nop 1
	v_add_f32_dpp v45, v45, v45 row_mirror row_mask:0xf bank_mask:0xf
	ds_bpermute_b32 v46, v100, v45
	s_waitcnt lgkmcnt(0)
	v_add_f32_e32 v45, v45, v46
	ds_bpermute_b32 v46, v101, v45
	s_waitcnt lgkmcnt(0)
	v_add_f32_e32 v45, v45, v46
	v_fmamk_f32 v45, v45, 0x3b800000, v166
	v_rsq_f32_e32 v46, v45
	s_nop 0
	v_pk_mul_f32 v[92:93], v[92:93], v[46:47] op_sel_hi:[1,0]
	v_pk_mul_f32 v[46:47], v[94:95], v[46:47] op_sel_hi:[1,0]
	v_pk_mul_f32 v[92:93], v[0:1], v[92:93]
	v_pk_mul_f32 v[46:47], v[2:3], v[46:47]
	v_lshlrev_b32_e32 v94, 16, v41
	v_and_b32_e32 v95, 0xffff0000, v41
	v_pk_mul_f32 v[40:41], v[104:105], v[104:105]
	v_cvt_pk_bf16_f32 v92, v92, v93
	v_cvt_pk_bf16_f32 v93, v46, v47
	v_pk_mul_f32 v[102:103], v[94:95], v[94:95]
	v_add_f32_e32 v40, v40, v41
	global_store_dwordx2 v[90:91], v[92:93], off offset:1536
	v_lshlrev_b32_e32 v92, 16, v42
	v_and_b32_e32 v93, 0xffff0000, v42
	v_add_f32_e32 v40, v102, v40
	v_lshlrev_b32_e32 v46, 16, v43
	v_and_b32_e32 v47, 0xffff0000, v43
	v_pk_mul_f32 v[42:43], v[92:93], v[92:93]
	v_add_f32_e32 v40, v103, v40
	v_add_f32_e32 v40, v42, v40
	v_pk_mul_f32 v[90:91], v[46:47], v[46:47]
	v_add_f32_e32 v40, v43, v40
	v_add_f32_e32 v40, v90, v40
	v_add_f32_e32 v40, v91, v40
	s_waitcnt lgkmcnt(0)
	s_nop 1
	v_add_f32_dpp v40, v40, v40 quad_perm:[1,0,3,2] row_mask:0xf bank_mask:0xf
	s_waitcnt lgkmcnt(0)
	s_nop 1
	v_add_f32_dpp v40, v40, v40 quad_perm:[2,3,0,1] row_mask:0xf bank_mask:0xf
	s_waitcnt lgkmcnt(0)
	s_nop 1
	v_add_f32_dpp v40, v40, v40 row_half_mirror row_mask:0xf bank_mask:0xf
	s_waitcnt lgkmcnt(0)
	s_nop 1
	v_add_f32_dpp v40, v40, v40 row_mirror row_mask:0xf bank_mask:0xf
	ds_bpermute_b32 v41, v100, v40
	s_waitcnt lgkmcnt(0)
	v_add_f32_e32 v40, v40, v41
	ds_bpermute_b32 v41, v101, v40
	s_waitcnt lgkmcnt(0)
	v_add_f32_e32 v40, v40, v41
	v_fmamk_f32 v40, v40, 0x3b000000, v166
	v_rsq_f32_e32 v40, v40
	s_nop 0
	v_pk_mul_f32 v[90:91], v[8:9], v[40:41] op_sel_hi:[1,0]
	v_pk_mul_f32 v[42:43], v[12:13], v[40:41] op_sel_hi:[1,0]
	v_pk_mul_f32 v[90:91], v[90:91], v[92:93]
	v_pk_mul_f32 v[92:93], v[14:15], v[40:41] op_sel_hi:[1,0]
	v_pk_mul_f32 v[40:41], v[10:11], v[40:41] op_sel_hi:[1,0]
	v_pk_mul_f32 v[42:43], v[42:43], v[104:105]
	v_pk_mul_f32 v[92:93], v[92:93], v[94:95]
	v_pk_mul_f32 v[46:47], v[40:41], v[46:47]
	v_cvt_pk_bf16_f32 v40, v42, v43
	v_cvt_pk_bf16_f32 v41, v92, v93
	v_cvt_pk_bf16_f32 v42, v90, v91
	v_cvt_pk_bf16_f32 v43, v46, v47
	v_lshlrev_b32_e32 v46, 16, v86
	v_and_b32_e32 v47, 0xffff0000, v86
	global_store_dwordx4 v[88:89], v[40:43], off
	v_lshlrev_b32_e32 v88, 16, v36
	v_and_b32_e32 v89, 0xffff0000, v36
	v_lshlrev_b32_e32 v40, 16, v87
	v_and_b32_e32 v41, 0xffff0000, v87
	v_pk_mul_f32 v[86:87], v[46:47], v[46:47]
	v_pk_mul_f32 v[42:43], v[40:41], v[40:41]
	v_add_f32_e32 v45, v86, v87
	v_add_f32_e32 v42, v42, v45
	v_add_f32_e32 v42, v43, v42
	v_add_u32_e32 v45, 0x404, v44
	s_waitcnt lgkmcnt(0)
	s_nop 1
	v_add_f32_dpp v42, v42, v42 quad_perm:[1,0,3,2] row_mask:0xf bank_mask:0xf
	s_waitcnt lgkmcnt(0)
	s_nop 1
	v_add_f32_dpp v42, v42, v42 quad_perm:[2,3,0,1] row_mask:0xf bank_mask:0xf
	s_waitcnt lgkmcnt(0)
	s_nop 1
	v_add_f32_dpp v42, v42, v42 row_half_mirror row_mask:0xf bank_mask:0xf
	s_waitcnt lgkmcnt(0)
	s_nop 1
	v_add_f32_dpp v42, v42, v42 row_mirror row_mask:0xf bank_mask:0xf
	ds_bpermute_b32 v43, v100, v42
	s_waitcnt lgkmcnt(0)
	v_add_f32_e32 v42, v42, v43
	ds_bpermute_b32 v43, v101, v42
	s_waitcnt lgkmcnt(0)
	v_add_f32_e32 v42, v42, v43
	v_fmamk_f32 v42, v42, 0x3b800000, v166
	v_rsq_f32_e32 v42, v42
	s_nop 0
	v_pk_mul_f32 v[46:47], v[42:43], v[46:47] op_sel_hi:[0,1]
	v_pk_mul_f32 v[40:41], v[42:43], v[40:41] op_sel_hi:[0,1]
	v_pk_mul_f32 v[46:47], v[4:5], v[46:47]
	v_pk_mul_f32 v[40:41], v[6:7], v[40:41]
	v_cvt_pk_bf16_f32 v46, v46, v47
	v_cvt_pk_bf16_f32 v47, v40, v41
	v_add_u32_e32 v40, 0x40c, v44
	global_store_dwordx2 v[84:85], v[46:47], off offset:1024
	ds_read2_b32 v[40:41], v40 offset1:1
	ds_read2_b32 v[46:47], v45 offset1:1
	s_waitcnt lgkmcnt(1)
	v_pk_mul_f32 v[42:43], v[40:41], v[40:41]
	s_waitcnt lgkmcnt(0)
	v_pk_mul_f32 v[86:87], v[46:47], v[46:47]
	s_nop 0
	v_add_f32_e32 v45, v86, v87
	v_add_f32_e32 v42, v45, v42
	v_add_f32_e32 v42, v42, v43
	s_waitcnt lgkmcnt(0)
	s_nop 1
	v_add_f32_dpp v42, v42, v42 quad_perm:[1,0,3,2] row_mask:0xf bank_mask:0xf
	s_waitcnt lgkmcnt(0)
	s_nop 1
	v_add_f32_dpp v42, v42, v42 quad_perm:[2,3,0,1] row_mask:0xf bank_mask:0xf
	s_waitcnt lgkmcnt(0)
	s_nop 1
	v_add_f32_dpp v42, v42, v42 row_half_mirror row_mask:0xf bank_mask:0xf
	s_waitcnt lgkmcnt(0)
	s_nop 1
	v_add_f32_dpp v42, v42, v42 row_mirror row_mask:0xf bank_mask:0xf
	ds_bpermute_b32 v43, v100, v42
	s_waitcnt lgkmcnt(0)
	v_add_f32_e32 v42, v42, v43
	ds_bpermute_b32 v43, v101, v42
	s_waitcnt lgkmcnt(0)
	v_add_f32_e32 v42, v42, v43
	v_fmamk_f32 v42, v42, 0x3b800000, v166
	v_rsq_f32_e32 v42, v42
	s_nop 0
	v_pk_mul_f32 v[46:47], v[46:47], v[42:43] op_sel_hi:[1,0]
	v_pk_mul_f32 v[40:41], v[40:41], v[42:43] op_sel_hi:[1,0]
	v_pk_mul_f32 v[46:47], v[0:1], v[46:47]
	v_pk_mul_f32 v[40:41], v[2:3], v[40:41]
	v_cvt_pk_bf16_f32 v46, v46, v47
	v_cvt_pk_bf16_f32 v47, v40, v41
	global_store_dwordx2 v[84:85], v[46:47], off offset:1536
	v_lshlrev_b32_e32 v84, 16, v37
	v_and_b32_e32 v85, 0xffff0000, v37
	v_pk_mul_f32 v[36:37], v[88:89], v[88:89]
	v_pk_mul_f32 v[86:87], v[84:85], v[84:85]
	v_add_f32_e32 v36, v36, v37
	v_lshlrev_b32_e32 v46, 16, v38
	v_and_b32_e32 v47, 0xffff0000, v38
	v_add_f32_e32 v36, v86, v36
	v_lshlrev_b32_e32 v40, 16, v39
	v_and_b32_e32 v41, 0xffff0000, v39
	v_pk_mul_f32 v[38:39], v[46:47], v[46:47]
	v_add_f32_e32 v36, v87, v36
	v_add_f32_e32 v36, v38, v36
	v_pk_mul_f32 v[42:43], v[40:41], v[40:41]
	v_add_f32_e32 v36, v39, v36
	v_add_f32_e32 v36, v42, v36
	v_add_f32_e32 v36, v43, v36
	s_waitcnt lgkmcnt(0)
	s_nop 1
	v_add_f32_dpp v36, v36, v36 quad_perm:[1,0,3,2] row_mask:0xf bank_mask:0xf
	s_waitcnt lgkmcnt(0)
	s_nop 1
	v_add_f32_dpp v36, v36, v36 quad_perm:[2,3,0,1] row_mask:0xf bank_mask:0xf
	s_waitcnt lgkmcnt(0)
	s_nop 1
	v_add_f32_dpp v36, v36, v36 row_half_mirror row_mask:0xf bank_mask:0xf
	s_waitcnt lgkmcnt(0)
	s_nop 1
	v_add_f32_dpp v36, v36, v36 row_mirror row_mask:0xf bank_mask:0xf
	ds_bpermute_b32 v37, v100, v36
	s_waitcnt lgkmcnt(0)
	v_add_f32_e32 v36, v36, v37
	ds_bpermute_b32 v37, v101, v36
	s_waitcnt lgkmcnt(0)
	v_add_f32_e32 v36, v36, v37
	v_fmamk_f32 v36, v36, 0x3b000000, v166
	v_rsq_f32_e32 v36, v36
	s_nop 0
	v_pk_mul_f32 v[42:43], v[8:9], v[36:37] op_sel_hi:[1,0]
	v_pk_mul_f32 v[38:39], v[12:13], v[36:37] op_sel_hi:[1,0]
	v_pk_mul_f32 v[42:43], v[42:43], v[46:47]
	v_pk_mul_f32 v[46:47], v[14:15], v[36:37] op_sel_hi:[1,0]
	v_pk_mul_f32 v[36:37], v[10:11], v[36:37] op_sel_hi:[1,0]
	v_pk_mul_f32 v[38:39], v[38:39], v[88:89]
	v_pk_mul_f32 v[46:47], v[46:47], v[84:85]
	v_pk_mul_f32 v[40:41], v[36:37], v[40:41]
	v_cvt_pk_bf16_f32 v36, v38, v39
	v_cvt_pk_bf16_f32 v37, v46, v47
	v_cvt_pk_bf16_f32 v38, v42, v43
	v_cvt_pk_bf16_f32 v39, v40, v41
	v_lshlrev_b32_e32 v40, 16, v80
	v_and_b32_e32 v41, 0xffff0000, v80
	global_store_dwordx4 v[82:83], v[36:39], off
	v_pk_mul_f32 v[42:43], v[40:41], v[40:41]
	s_nop 0
	v_lshlrev_b32_e32 v36, 16, v81
	v_and_b32_e32 v37, 0xffff0000, v81
	v_pk_mul_f32 v[38:39], v[36:37], v[36:37]
	v_add_f32_e32 v42, v42, v43
	v_add_f32_e32 v38, v38, v42
	v_add_f32_e32 v38, v39, v38
	s_waitcnt lgkmcnt(0)
	s_nop 1
	v_add_f32_dpp v38, v38, v38 quad_perm:[1,0,3,2] row_mask:0xf bank_mask:0xf
	s_waitcnt lgkmcnt(0)
	s_nop 1
	v_add_f32_dpp v38, v38, v38 quad_perm:[2,3,0,1] row_mask:0xf bank_mask:0xf
	s_waitcnt lgkmcnt(0)
	s_nop 1
	v_add_f32_dpp v38, v38, v38 row_half_mirror row_mask:0xf bank_mask:0xf
	s_waitcnt lgkmcnt(0)
	s_nop 1
	v_add_f32_dpp v38, v38, v38 row_mirror row_mask:0xf bank_mask:0xf
	ds_bpermute_b32 v39, v100, v38
	s_waitcnt lgkmcnt(0)
	v_add_f32_e32 v38, v38, v39
	ds_bpermute_b32 v39, v101, v38
	s_waitcnt lgkmcnt(0)
	v_add_f32_e32 v38, v38, v39
	v_fmamk_f32 v38, v38, 0x3b800000, v166
	v_rsq_f32_e32 v38, v38
	s_nop 0
	v_pk_mul_f32 v[40:41], v[38:39], v[40:41] op_sel_hi:[0,1]
	v_pk_mul_f32 v[36:37], v[38:39], v[36:37] op_sel_hi:[0,1]
	v_pk_mul_f32 v[40:41], v[4:5], v[40:41]
	v_pk_mul_f32 v[36:37], v[6:7], v[36:37]
	v_cvt_pk_bf16_f32 v40, v40, v41
	v_cvt_pk_bf16_f32 v41, v36, v37
	v_add_u32_e32 v36, 0x808, v44
	ds_read2_b64 v[36:39], v36 offset1:1
	global_store_dwordx2 v[78:79], v[40:41], off offset:1024
	s_waitcnt lgkmcnt(0)
	v_pk_mul_f32 v[42:43], v[36:37], v[36:37]
	v_pk_mul_f32 v[40:41], v[38:39], v[38:39]
	v_add_f32_e32 v42, v42, v43
	v_add_f32_e32 v40, v42, v40
	v_add_f32_e32 v40, v40, v41
	v_lshlrev_b32_e32 v42, 16, v33
	v_and_b32_e32 v43, 0xffff0000, v33
	v_pk_mul_f32 v[46:47], v[42:43], v[42:43]
	s_waitcnt lgkmcnt(0)
	s_nop 1
	v_add_f32_dpp v40, v40, v40 quad_perm:[1,0,3,2] row_mask:0xf bank_mask:0xf
	s_waitcnt lgkmcnt(0)
	s_nop 1
	v_add_f32_dpp v40, v40, v40 quad_perm:[2,3,0,1] row_mask:0xf bank_mask:0xf
	s_waitcnt lgkmcnt(0)
	s_nop 1
	v_add_f32_dpp v40, v40, v40 row_half_mirror row_mask:0xf bank_mask:0xf
	s_waitcnt lgkmcnt(0)
	s_nop 1
	v_add_f32_dpp v40, v40, v40 row_mirror row_mask:0xf bank_mask:0xf
	ds_bpermute_b32 v41, v100, v40
	s_waitcnt lgkmcnt(0)
	v_add_f32_e32 v40, v40, v41
	ds_bpermute_b32 v41, v101, v40
	s_waitcnt lgkmcnt(0)
	v_add_f32_e32 v40, v40, v41
	v_fmamk_f32 v40, v40, 0x3b800000, v166
	v_rsq_f32_e32 v40, v40
	s_nop 0
	v_pk_mul_f32 v[36:37], v[36:37], v[40:41] op_sel_hi:[1,0]
	v_pk_mul_f32 v[38:39], v[38:39], v[40:41] op_sel_hi:[1,0]
	v_pk_mul_f32 v[36:37], v[0:1], v[36:37]
	v_pk_mul_f32 v[38:39], v[2:3], v[38:39]
	v_cvt_pk_bf16_f32 v36, v36, v37
	v_cvt_pk_bf16_f32 v37, v38, v39
	global_store_dwordx2 v[78:79], v[36:37], off offset:1536
	v_lshlrev_b32_e32 v78, 16, v32
	v_and_b32_e32 v79, 0xffff0000, v32
	v_pk_mul_f32 v[32:33], v[78:79], v[78:79]
	v_lshlrev_b32_e32 v40, 16, v34
	v_add_f32_e32 v32, v32, v33
	v_and_b32_e32 v41, 0xffff0000, v34
	v_add_f32_e32 v32, v46, v32
	v_lshlrev_b32_e32 v36, 16, v35
	v_and_b32_e32 v37, 0xffff0000, v35
	v_pk_mul_f32 v[34:35], v[40:41], v[40:41]
	v_add_f32_e32 v32, v47, v32
	v_add_f32_e32 v32, v34, v32
	v_pk_mul_f32 v[38:39], v[36:37], v[36:37]
	v_add_f32_e32 v32, v35, v32
	v_add_f32_e32 v32, v38, v32
	v_add_f32_e32 v32, v39, v32
	s_waitcnt lgkmcnt(0)
	s_nop 1
	v_add_f32_dpp v32, v32, v32 quad_perm:[1,0,3,2] row_mask:0xf bank_mask:0xf
	s_waitcnt lgkmcnt(0)
	s_nop 1
	v_add_f32_dpp v32, v32, v32 quad_perm:[2,3,0,1] row_mask:0xf bank_mask:0xf
	s_waitcnt lgkmcnt(0)
	s_nop 1
	v_add_f32_dpp v32, v32, v32 row_half_mirror row_mask:0xf bank_mask:0xf
	s_waitcnt lgkmcnt(0)
	s_nop 1
	v_add_f32_dpp v32, v32, v32 row_mirror row_mask:0xf bank_mask:0xf
	ds_bpermute_b32 v33, v100, v32
	s_waitcnt lgkmcnt(0)
	v_add_f32_e32 v32, v32, v33
	ds_bpermute_b32 v33, v101, v32
	s_waitcnt lgkmcnt(0)
	v_add_f32_e32 v32, v32, v33
	v_fmamk_f32 v32, v32, 0x3b000000, v166
	v_rsq_f32_e32 v32, v32
	s_nop 0
	v_pk_mul_f32 v[38:39], v[8:9], v[32:33] op_sel_hi:[1,0]
	v_pk_mul_f32 v[34:35], v[12:13], v[32:33] op_sel_hi:[1,0]
	v_pk_mul_f32 v[38:39], v[38:39], v[40:41]
	v_pk_mul_f32 v[40:41], v[14:15], v[32:33] op_sel_hi:[1,0]
	v_pk_mul_f32 v[32:33], v[10:11], v[32:33] op_sel_hi:[1,0]
	v_pk_mul_f32 v[34:35], v[34:35], v[78:79]
	v_pk_mul_f32 v[40:41], v[40:41], v[42:43]
	v_pk_mul_f32 v[36:37], v[32:33], v[36:37]
	v_cvt_pk_bf16_f32 v32, v34, v35
	v_cvt_pk_bf16_f32 v33, v40, v41
	v_cvt_pk_bf16_f32 v34, v38, v39
	v_cvt_pk_bf16_f32 v35, v36, v37
	v_lshlrev_b32_e32 v36, 16, v74
	v_and_b32_e32 v37, 0xffff0000, v74
	global_store_dwordx4 v[76:77], v[32:35], off
	v_pk_mul_f32 v[38:39], v[36:37], v[36:37]
	v_lshlrev_b32_e32 v42, 16, v28
	v_lshlrev_b32_e32 v32, 16, v75
	v_and_b32_e32 v33, 0xffff0000, v75
	v_pk_mul_f32 v[34:35], v[32:33], v[32:33]
	v_add_f32_e32 v38, v38, v39
	v_add_f32_e32 v34, v34, v38
	v_add_f32_e32 v34, v35, v34
	v_and_b32_e32 v43, 0xffff0000, v28
	s_waitcnt lgkmcnt(0)
	s_nop 1
	v_add_f32_dpp v34, v34, v34 quad_perm:[1,0,3,2] row_mask:0xf bank_mask:0xf
	s_waitcnt lgkmcnt(0)
	s_nop 1
	v_add_f32_dpp v34, v34, v34 quad_perm:[2,3,0,1] row_mask:0xf bank_mask:0xf
	s_waitcnt lgkmcnt(0)
	s_nop 1
	v_add_f32_dpp v34, v34, v34 row_half_mirror row_mask:0xf bank_mask:0xf
	s_waitcnt lgkmcnt(0)
	s_nop 1
	v_add_f32_dpp v34, v34, v34 row_mirror row_mask:0xf bank_mask:0xf
	ds_bpermute_b32 v35, v100, v34
	s_waitcnt lgkmcnt(0)
	v_add_f32_e32 v34, v34, v35
	ds_bpermute_b32 v35, v101, v34
	s_waitcnt lgkmcnt(0)
	v_add_f32_e32 v34, v34, v35
	v_fmamk_f32 v34, v34, 0x3b800000, v166
	v_rsq_f32_e32 v34, v34
	s_nop 0
	v_pk_mul_f32 v[36:37], v[34:35], v[36:37] op_sel_hi:[0,1]
	v_pk_mul_f32 v[32:33], v[34:35], v[32:33] op_sel_hi:[0,1]
	v_pk_mul_f32 v[36:37], v[4:5], v[36:37]
	v_pk_mul_f32 v[32:33], v[6:7], v[32:33]
	v_cvt_pk_bf16_f32 v36, v36, v37
	v_cvt_pk_bf16_f32 v37, v32, v33
	global_store_dwordx2 v[72:73], v[36:37], off offset:1024
	v_add_u32_e32 v36, 0xc0c, v44
	v_add_u32_e32 v32, 0xc14, v44
	ds_read2_b32 v[32:33], v32 offset1:1
	ds_read2_b32 v[36:37], v36 offset1:1
	s_waitcnt lgkmcnt(1)
	v_pk_mul_f32 v[34:35], v[32:33], v[32:33]
	s_waitcnt lgkmcnt(0)
	v_pk_mul_f32 v[38:39], v[36:37], v[36:37]
	s_nop 0
	v_add_f32_e32 v38, v38, v39
	v_add_f32_e32 v34, v38, v34
	v_add_f32_e32 v34, v34, v35
	v_lshlrev_b32_e32 v38, 16, v29
	v_and_b32_e32 v39, 0xffff0000, v29
	v_pk_mul_f32 v[28:29], v[42:43], v[42:43]
	v_pk_mul_f32 v[40:41], v[38:39], v[38:39]
	s_waitcnt lgkmcnt(0)
	s_nop 1
	v_add_f32_dpp v34, v34, v34 quad_perm:[1,0,3,2] row_mask:0xf bank_mask:0xf
	v_add_f32_e32 v28, v28, v29
	v_add_f32_e32 v28, v40, v28
	v_add_f32_e32 v28, v41, v28
	s_waitcnt lgkmcnt(0)
	s_nop 1
	v_add_f32_dpp v34, v34, v34 quad_perm:[2,3,0,1] row_mask:0xf bank_mask:0xf
	s_waitcnt lgkmcnt(0)
	s_nop 1
	v_add_f32_dpp v34, v34, v34 row_half_mirror row_mask:0xf bank_mask:0xf
	s_waitcnt lgkmcnt(0)
	s_nop 1
	v_add_f32_dpp v34, v34, v34 row_mirror row_mask:0xf bank_mask:0xf
	ds_bpermute_b32 v35, v100, v34
	s_waitcnt lgkmcnt(0)
	v_add_f32_e32 v34, v34, v35
	ds_bpermute_b32 v35, v101, v34
	s_waitcnt lgkmcnt(0)
	v_add_f32_e32 v34, v34, v35
	v_fmamk_f32 v34, v34, 0x3b800000, v166
	v_rsq_f32_e32 v34, v34
	s_nop 0
	v_pk_mul_f32 v[36:37], v[36:37], v[34:35] op_sel_hi:[1,0]
	v_pk_mul_f32 v[32:33], v[32:33], v[34:35] op_sel_hi:[1,0]
	v_pk_mul_f32 v[36:37], v[0:1], v[36:37]
	v_pk_mul_f32 v[32:33], v[2:3], v[32:33]
	v_cvt_pk_bf16_f32 v36, v36, v37
	v_cvt_pk_bf16_f32 v37, v32, v33
	global_store_dwordx2 v[72:73], v[36:37], off offset:1536
	v_lshlrev_b32_e32 v36, 16, v30
	v_and_b32_e32 v37, 0xffff0000, v30
	v_lshlrev_b32_e32 v32, 16, v31
	v_and_b32_e32 v33, 0xffff0000, v31
	v_pk_mul_f32 v[30:31], v[36:37], v[36:37]
	v_pk_mul_f32 v[34:35], v[32:33], v[32:33]
	v_add_f32_e32 v28, v30, v28
	v_add_f32_e32 v28, v31, v28
	v_add_f32_e32 v28, v34, v28
	v_add_f32_e32 v28, v35, v28
	s_waitcnt lgkmcnt(0)
	s_nop 1
	v_add_f32_dpp v28, v28, v28 quad_perm:[1,0,3,2] row_mask:0xf bank_mask:0xf
	s_waitcnt lgkmcnt(0)
	s_nop 1
	v_add_f32_dpp v28, v28, v28 quad_perm:[2,3,0,1] row_mask:0xf bank_mask:0xf
	s_waitcnt lgkmcnt(0)
	s_nop 1
	v_add_f32_dpp v28, v28, v28 row_half_mirror row_mask:0xf bank_mask:0xf
	s_waitcnt lgkmcnt(0)
	s_nop 1
	v_add_f32_dpp v28, v28, v28 row_mirror row_mask:0xf bank_mask:0xf
	ds_bpermute_b32 v29, v100, v28
	s_waitcnt lgkmcnt(0)
	v_add_f32_e32 v28, v28, v29
	ds_bpermute_b32 v29, v101, v28
	s_waitcnt lgkmcnt(0)
	v_add_f32_e32 v28, v28, v29
	v_fmamk_f32 v28, v28, 0x3b000000, v166
	v_rsq_f32_e32 v28, v28
	s_nop 0
	v_pk_mul_f32 v[34:35], v[8:9], v[28:29] op_sel_hi:[1,0]
	v_pk_mul_f32 v[30:31], v[12:13], v[28:29] op_sel_hi:[1,0]
	v_pk_mul_f32 v[34:35], v[34:35], v[36:37]
	v_pk_mul_f32 v[36:37], v[14:15], v[28:29] op_sel_hi:[1,0]
	v_pk_mul_f32 v[28:29], v[10:11], v[28:29] op_sel_hi:[1,0]
	v_pk_mul_f32 v[30:31], v[30:31], v[42:43]
	v_pk_mul_f32 v[36:37], v[36:37], v[38:39]
	v_pk_mul_f32 v[32:33], v[28:29], v[32:33]
	v_cvt_pk_bf16_f32 v28, v30, v31
	v_cvt_pk_bf16_f32 v29, v36, v37
	v_cvt_pk_bf16_f32 v30, v34, v35
	v_cvt_pk_bf16_f32 v31, v32, v33
	v_lshlrev_b32_e32 v32, 16, v68
	v_and_b32_e32 v33, 0xffff0000, v68
	global_store_dwordx4 v[70:71], v[28:31], off
	v_pk_mul_f32 v[34:35], v[32:33], v[32:33]
	v_lshlrev_b32_e32 v38, 16, v24
	v_lshlrev_b32_e32 v28, 16, v69
	v_and_b32_e32 v29, 0xffff0000, v69
	v_pk_mul_f32 v[30:31], v[28:29], v[28:29]
	v_add_f32_e32 v34, v34, v35
	v_add_f32_e32 v30, v30, v34
	v_add_f32_e32 v30, v31, v30
	v_and_b32_e32 v39, 0xffff0000, v24
	s_waitcnt lgkmcnt(0)
	s_nop 1
	v_add_f32_dpp v30, v30, v30 quad_perm:[1,0,3,2] row_mask:0xf bank_mask:0xf
	s_waitcnt lgkmcnt(0)
	s_nop 1
	v_add_f32_dpp v30, v30, v30 quad_perm:[2,3,0,1] row_mask:0xf bank_mask:0xf
	s_waitcnt lgkmcnt(0)
	s_nop 1
	v_add_f32_dpp v30, v30, v30 row_half_mirror row_mask:0xf bank_mask:0xf
	s_waitcnt lgkmcnt(0)
	s_nop 1
	v_add_f32_dpp v30, v30, v30 row_mirror row_mask:0xf bank_mask:0xf
	ds_bpermute_b32 v31, v100, v30
	s_waitcnt lgkmcnt(0)
	v_add_f32_e32 v30, v30, v31
	ds_bpermute_b32 v31, v101, v30
	s_waitcnt lgkmcnt(0)
	v_add_f32_e32 v30, v30, v31
	v_fmamk_f32 v30, v30, 0x3b800000, v166
	v_rsq_f32_e32 v30, v30
	s_nop 0
	v_pk_mul_f32 v[32:33], v[30:31], v[32:33] op_sel_hi:[0,1]
	v_pk_mul_f32 v[28:29], v[30:31], v[28:29] op_sel_hi:[0,1]
	v_pk_mul_f32 v[32:33], v[4:5], v[32:33]
	v_pk_mul_f32 v[28:29], v[6:7], v[28:29]
	v_cvt_pk_bf16_f32 v32, v32, v33
	v_cvt_pk_bf16_f32 v33, v28, v29
	ds_read_b128 v[28:31], v44 offset:4112
	global_store_dwordx2 v[66:67], v[32:33], off offset:1024
	s_waitcnt lgkmcnt(0)
	v_pk_mul_f32 v[34:35], v[28:29], v[28:29]
	v_pk_mul_f32 v[32:33], v[30:31], v[30:31]
	v_add_f32_e32 v34, v34, v35
	v_add_f32_e32 v32, v34, v32
	v_add_f32_e32 v32, v32, v33
	v_lshlrev_b32_e32 v34, 16, v25
	v_and_b32_e32 v35, 0xffff0000, v25
	v_pk_mul_f32 v[24:25], v[38:39], v[38:39]
	v_pk_mul_f32 v[36:37], v[34:35], v[34:35]
	s_waitcnt lgkmcnt(0)
	s_nop 1
	v_add_f32_dpp v32, v32, v32 quad_perm:[1,0,3,2] row_mask:0xf bank_mask:0xf
	v_add_f32_e32 v24, v24, v25
	v_add_f32_e32 v24, v36, v24
	v_add_f32_e32 v24, v37, v24
	s_waitcnt lgkmcnt(0)
	s_nop 1
	v_add_f32_dpp v32, v32, v32 quad_perm:[2,3,0,1] row_mask:0xf bank_mask:0xf
	s_waitcnt lgkmcnt(0)
	s_nop 1
	v_add_f32_dpp v32, v32, v32 row_half_mirror row_mask:0xf bank_mask:0xf
	s_waitcnt lgkmcnt(0)
	s_nop 1
	v_add_f32_dpp v32, v32, v32 row_mirror row_mask:0xf bank_mask:0xf
	ds_bpermute_b32 v33, v100, v32
	s_waitcnt lgkmcnt(0)
	v_add_f32_e32 v32, v32, v33
	ds_bpermute_b32 v33, v101, v32
	s_waitcnt lgkmcnt(0)
	v_add_f32_e32 v32, v32, v33
	v_fmamk_f32 v32, v32, 0x3b800000, v166
	v_rsq_f32_e32 v32, v32
	s_nop 0
	v_pk_mul_f32 v[28:29], v[28:29], v[32:33] op_sel_hi:[1,0]
	v_pk_mul_f32 v[30:31], v[30:31], v[32:33] op_sel_hi:[1,0]
	v_pk_mul_f32 v[28:29], v[0:1], v[28:29]
	v_pk_mul_f32 v[30:31], v[2:3], v[30:31]
	v_cvt_pk_bf16_f32 v28, v28, v29
	v_cvt_pk_bf16_f32 v29, v30, v31
	v_lshlrev_b32_e32 v32, 16, v26
	v_and_b32_e32 v33, 0xffff0000, v26
	global_store_dwordx2 v[66:67], v[28:29], off offset:1536
	v_lshlrev_b32_e32 v28, 16, v27
	v_and_b32_e32 v29, 0xffff0000, v27
	v_pk_mul_f32 v[26:27], v[32:33], v[32:33]
	v_pk_mul_f32 v[30:31], v[28:29], v[28:29]
	v_add_f32_e32 v24, v26, v24
	v_add_f32_e32 v24, v27, v24
	v_add_f32_e32 v24, v30, v24
	v_add_f32_e32 v24, v31, v24
	s_waitcnt lgkmcnt(0)
	s_nop 1
	v_add_f32_dpp v24, v24, v24 quad_perm:[1,0,3,2] row_mask:0xf bank_mask:0xf
	s_waitcnt lgkmcnt(0)
	s_nop 1
	v_add_f32_dpp v24, v24, v24 quad_perm:[2,3,0,1] row_mask:0xf bank_mask:0xf
	s_waitcnt lgkmcnt(0)
	s_nop 1
	v_add_f32_dpp v24, v24, v24 row_half_mirror row_mask:0xf bank_mask:0xf
	s_waitcnt lgkmcnt(0)
	s_nop 1
	v_add_f32_dpp v24, v24, v24 row_mirror row_mask:0xf bank_mask:0xf
	ds_bpermute_b32 v25, v100, v24
	s_waitcnt lgkmcnt(0)
	v_add_f32_e32 v24, v24, v25
	ds_bpermute_b32 v25, v101, v24
	s_waitcnt lgkmcnt(0)
	v_add_f32_e32 v24, v24, v25
	v_fmamk_f32 v24, v24, 0x3b000000, v166
	v_rsq_f32_e32 v24, v24
	s_nop 0
	v_pk_mul_f32 v[30:31], v[8:9], v[24:25] op_sel_hi:[1,0]
	v_pk_mul_f32 v[26:27], v[12:13], v[24:25] op_sel_hi:[1,0]
	v_pk_mul_f32 v[30:31], v[30:31], v[32:33]
	v_pk_mul_f32 v[32:33], v[14:15], v[24:25] op_sel_hi:[1,0]
	v_pk_mul_f32 v[24:25], v[10:11], v[24:25] op_sel_hi:[1,0]
	v_pk_mul_f32 v[26:27], v[26:27], v[38:39]
	v_pk_mul_f32 v[32:33], v[32:33], v[34:35]
	v_pk_mul_f32 v[28:29], v[24:25], v[28:29]
	v_cvt_pk_bf16_f32 v24, v26, v27
	v_cvt_pk_bf16_f32 v25, v32, v33
	v_cvt_pk_bf16_f32 v26, v30, v31
	v_cvt_pk_bf16_f32 v27, v28, v29
	v_lshlrev_b32_e32 v28, 16, v62
	v_and_b32_e32 v29, 0xffff0000, v62
	global_store_dwordx4 v[64:65], v[24:27], off
	v_pk_mul_f32 v[30:31], v[28:29], v[28:29]
	v_lshlrev_b32_e32 v34, 16, v20
	v_lshlrev_b32_e32 v24, 16, v63
	v_and_b32_e32 v25, 0xffff0000, v63
	v_pk_mul_f32 v[26:27], v[24:25], v[24:25]
	v_add_f32_e32 v30, v30, v31
	v_add_f32_e32 v26, v26, v30
	v_add_f32_e32 v26, v27, v26
	v_and_b32_e32 v35, 0xffff0000, v20
	s_waitcnt lgkmcnt(0)
	s_nop 1
	v_add_f32_dpp v26, v26, v26 quad_perm:[1,0,3,2] row_mask:0xf bank_mask:0xf
	s_waitcnt lgkmcnt(0)
	s_nop 1
	v_add_f32_dpp v26, v26, v26 quad_perm:[2,3,0,1] row_mask:0xf bank_mask:0xf
	s_waitcnt lgkmcnt(0)
	s_nop 1
	v_add_f32_dpp v26, v26, v26 row_half_mirror row_mask:0xf bank_mask:0xf
	s_waitcnt lgkmcnt(0)
	s_nop 1
	v_add_f32_dpp v26, v26, v26 row_mirror row_mask:0xf bank_mask:0xf
	ds_bpermute_b32 v27, v100, v26
	s_waitcnt lgkmcnt(0)
	v_add_f32_e32 v26, v26, v27
	ds_bpermute_b32 v27, v101, v26
	s_waitcnt lgkmcnt(0)
	v_add_f32_e32 v26, v26, v27
	v_fmamk_f32 v26, v26, 0x3b800000, v166
	v_rsq_f32_e32 v26, v26
	s_nop 0
	v_pk_mul_f32 v[28:29], v[26:27], v[28:29] op_sel_hi:[0,1]
	v_pk_mul_f32 v[24:25], v[26:27], v[24:25] op_sel_hi:[0,1]
	v_pk_mul_f32 v[28:29], v[4:5], v[28:29]
	v_pk_mul_f32 v[24:25], v[6:7], v[24:25]
	v_cvt_pk_bf16_f32 v28, v28, v29
	v_cvt_pk_bf16_f32 v29, v24, v25
	global_store_dwordx2 v[60:61], v[28:29], off offset:1024
	v_add_u32_e32 v28, 0x1414, v44
	v_add_u32_e32 v24, 0x141c, v44
	ds_read2_b32 v[24:25], v24 offset1:1
	ds_read2_b32 v[28:29], v28 offset1:1
	s_waitcnt lgkmcnt(1)
	v_pk_mul_f32 v[26:27], v[24:25], v[24:25]
	s_waitcnt lgkmcnt(0)
	v_pk_mul_f32 v[30:31], v[28:29], v[28:29]
	s_nop 0
	v_add_f32_e32 v30, v30, v31
	v_add_f32_e32 v26, v30, v26
	v_add_f32_e32 v26, v26, v27
	v_lshlrev_b32_e32 v30, 16, v21
	v_and_b32_e32 v31, 0xffff0000, v21
	v_pk_mul_f32 v[20:21], v[34:35], v[34:35]
	v_pk_mul_f32 v[32:33], v[30:31], v[30:31]
	s_waitcnt lgkmcnt(0)
	s_nop 1
	v_add_f32_dpp v26, v26, v26 quad_perm:[1,0,3,2] row_mask:0xf bank_mask:0xf
	v_add_f32_e32 v20, v20, v21
	v_add_f32_e32 v20, v32, v20
	v_add_f32_e32 v20, v33, v20
	s_waitcnt lgkmcnt(0)
	s_nop 1
	v_add_f32_dpp v26, v26, v26 quad_perm:[2,3,0,1] row_mask:0xf bank_mask:0xf
	s_waitcnt lgkmcnt(0)
	s_nop 1
	v_add_f32_dpp v26, v26, v26 row_half_mirror row_mask:0xf bank_mask:0xf
	s_waitcnt lgkmcnt(0)
	s_nop 1
	v_add_f32_dpp v26, v26, v26 row_mirror row_mask:0xf bank_mask:0xf
	ds_bpermute_b32 v27, v100, v26
	s_waitcnt lgkmcnt(0)
	v_add_f32_e32 v26, v26, v27
	ds_bpermute_b32 v27, v101, v26
	s_waitcnt lgkmcnt(0)
	v_add_f32_e32 v26, v26, v27
	v_fmamk_f32 v26, v26, 0x3b800000, v166
	v_rsq_f32_e32 v26, v26
	s_nop 0
	v_pk_mul_f32 v[28:29], v[28:29], v[26:27] op_sel_hi:[1,0]
	v_pk_mul_f32 v[24:25], v[24:25], v[26:27] op_sel_hi:[1,0]
	v_pk_mul_f32 v[28:29], v[0:1], v[28:29]
	v_pk_mul_f32 v[24:25], v[2:3], v[24:25]
	v_cvt_pk_bf16_f32 v28, v28, v29
	v_cvt_pk_bf16_f32 v29, v24, v25
	global_store_dwordx2 v[60:61], v[28:29], off offset:1536
	v_lshlrev_b32_e32 v28, 16, v22
	v_and_b32_e32 v29, 0xffff0000, v22
	v_lshlrev_b32_e32 v24, 16, v23
	v_and_b32_e32 v25, 0xffff0000, v23
	v_pk_mul_f32 v[22:23], v[28:29], v[28:29]
	v_pk_mul_f32 v[26:27], v[24:25], v[24:25]
	v_add_f32_e32 v20, v22, v20
	v_add_f32_e32 v20, v23, v20
	v_add_f32_e32 v20, v26, v20
	v_add_f32_e32 v20, v27, v20
	s_waitcnt lgkmcnt(0)
	s_nop 1
	v_add_f32_dpp v20, v20, v20 quad_perm:[1,0,3,2] row_mask:0xf bank_mask:0xf
	s_waitcnt lgkmcnt(0)
	s_nop 1
	v_add_f32_dpp v20, v20, v20 quad_perm:[2,3,0,1] row_mask:0xf bank_mask:0xf
	s_waitcnt lgkmcnt(0)
	s_nop 1
	v_add_f32_dpp v20, v20, v20 row_half_mirror row_mask:0xf bank_mask:0xf
	s_waitcnt lgkmcnt(0)
	s_nop 1
	v_add_f32_dpp v20, v20, v20 row_mirror row_mask:0xf bank_mask:0xf
	ds_bpermute_b32 v21, v100, v20
	s_waitcnt lgkmcnt(0)
	v_add_f32_e32 v20, v20, v21
	ds_bpermute_b32 v21, v101, v20
	s_waitcnt lgkmcnt(0)
	v_add_f32_e32 v20, v20, v21
	v_fmamk_f32 v20, v20, 0x3b000000, v166
	v_rsq_f32_e32 v20, v20
	s_nop 0
	v_pk_mul_f32 v[26:27], v[8:9], v[20:21] op_sel_hi:[1,0]
	v_pk_mul_f32 v[22:23], v[12:13], v[20:21] op_sel_hi:[1,0]
	v_pk_mul_f32 v[26:27], v[26:27], v[28:29]
	v_pk_mul_f32 v[28:29], v[14:15], v[20:21] op_sel_hi:[1,0]
	v_pk_mul_f32 v[20:21], v[10:11], v[20:21] op_sel_hi:[1,0]
	v_pk_mul_f32 v[22:23], v[22:23], v[34:35]
	v_pk_mul_f32 v[28:29], v[28:29], v[30:31]
	v_pk_mul_f32 v[24:25], v[20:21], v[24:25]
	v_cvt_pk_bf16_f32 v20, v22, v23
	v_cvt_pk_bf16_f32 v21, v28, v29
	v_cvt_pk_bf16_f32 v22, v26, v27
	v_cvt_pk_bf16_f32 v23, v24, v25
	v_lshlrev_b32_e32 v24, 16, v56
	v_and_b32_e32 v25, 0xffff0000, v56
	global_store_dwordx4 v[58:59], v[20:23], off
	v_pk_mul_f32 v[26:27], v[24:25], v[24:25]
	v_lshlrev_b32_e32 v34, 16, v16
	v_lshlrev_b32_e32 v20, 16, v57
	v_and_b32_e32 v21, 0xffff0000, v57
	v_pk_mul_f32 v[22:23], v[20:21], v[20:21]
	v_add_f32_e32 v26, v26, v27
	v_add_f32_e32 v22, v22, v26
	v_add_f32_e32 v22, v23, v22
	v_and_b32_e32 v35, 0xffff0000, v16
	v_lshlrev_b32_e32 v30, 16, v17
	v_and_b32_e32 v31, 0xffff0000, v17
	v_pk_mul_f32 v[16:17], v[34:35], v[34:35]
	s_waitcnt lgkmcnt(0)
	s_nop 1
	v_add_f32_dpp v22, v22, v22 quad_perm:[1,0,3,2] row_mask:0xf bank_mask:0xf
	v_pk_mul_f32 v[32:33], v[30:31], v[30:31]
	v_add_f32_e32 v16, v16, v17
	v_lshlrev_b32_e32 v28, 16, v18
	v_and_b32_e32 v29, 0xffff0000, v18
	s_waitcnt lgkmcnt(0)
	s_nop 1
	v_add_f32_dpp v22, v22, v22 quad_perm:[2,3,0,1] row_mask:0xf bank_mask:0xf
	v_add_f32_e32 v16, v32, v16
	v_add_f32_e32 v16, v33, v16
	s_waitcnt lgkmcnt(0)
	s_nop 1
	v_add_f32_dpp v22, v22, v22 row_half_mirror row_mask:0xf bank_mask:0xf
	s_waitcnt lgkmcnt(0)
	s_nop 1
	v_add_f32_dpp v22, v22, v22 row_mirror row_mask:0xf bank_mask:0xf
	ds_bpermute_b32 v23, v100, v22
	s_waitcnt lgkmcnt(0)
	v_add_f32_e32 v22, v22, v23
	ds_bpermute_b32 v23, v101, v22
	s_waitcnt lgkmcnt(0)
	v_add_f32_e32 v22, v22, v23
	v_fmamk_f32 v22, v22, 0x3b800000, v166
	v_rsq_f32_e32 v22, v22
	s_nop 0
	v_pk_mul_f32 v[24:25], v[22:23], v[24:25] op_sel_hi:[0,1]
	v_pk_mul_f32 v[20:21], v[22:23], v[20:21] op_sel_hi:[0,1]
	v_pk_mul_f32 v[24:25], v[4:5], v[24:25]
	v_pk_mul_f32 v[20:21], v[6:7], v[20:21]
	v_cvt_pk_bf16_f32 v24, v24, v25
	v_cvt_pk_bf16_f32 v25, v20, v21
	v_add_u32_e32 v20, 0x1818, v44
	ds_read2_b64 v[20:23], v20 offset1:1
	global_store_dwordx2 v[54:55], v[24:25], off offset:1024
	s_waitcnt lgkmcnt(0)
	v_pk_mul_f32 v[26:27], v[20:21], v[20:21]
	v_pk_mul_f32 v[24:25], v[22:23], v[22:23]
	v_add_f32_e32 v26, v26, v27
	v_add_f32_e32 v24, v26, v24
	v_add_f32_e32 v24, v24, v25
	s_waitcnt lgkmcnt(0)
	s_nop 1
	v_add_f32_dpp v24, v24, v24 quad_perm:[1,0,3,2] row_mask:0xf bank_mask:0xf
	s_waitcnt lgkmcnt(0)
	s_nop 1
	v_add_f32_dpp v24, v24, v24 quad_perm:[2,3,0,1] row_mask:0xf bank_mask:0xf
	s_waitcnt lgkmcnt(0)
	s_nop 1
	v_add_f32_dpp v24, v24, v24 row_half_mirror row_mask:0xf bank_mask:0xf
	s_waitcnt lgkmcnt(0)
	s_nop 1
	v_add_f32_dpp v24, v24, v24 row_mirror row_mask:0xf bank_mask:0xf
	ds_bpermute_b32 v25, v100, v24
	s_waitcnt lgkmcnt(0)
	v_add_f32_e32 v24, v24, v25
	ds_bpermute_b32 v25, v101, v24
	s_waitcnt lgkmcnt(0)
	v_add_f32_e32 v24, v24, v25
	v_fmamk_f32 v24, v24, 0x3b800000, v166
	v_rsq_f32_e32 v24, v24
	s_nop 0
	v_pk_mul_f32 v[20:21], v[20:21], v[24:25] op_sel_hi:[1,0]
	v_pk_mul_f32 v[22:23], v[22:23], v[24:25] op_sel_hi:[1,0]
	v_lshlrev_b32_e32 v24, 16, v19
	v_and_b32_e32 v25, 0xffff0000, v19
	v_pk_mul_f32 v[18:19], v[28:29], v[28:29]
	v_pk_mul_f32 v[26:27], v[24:25], v[24:25]
	v_add_f32_e32 v16, v18, v16
	v_add_f32_e32 v16, v19, v16
	v_add_f32_e32 v16, v26, v16
	v_add_f32_e32 v16, v27, v16
	v_pk_mul_f32 v[20:21], v[0:1], v[20:21]
	v_pk_mul_f32 v[22:23], v[2:3], v[22:23]
	v_cvt_pk_bf16_f32 v20, v20, v21
	v_cvt_pk_bf16_f32 v21, v22, v23
	s_waitcnt lgkmcnt(0)
	s_nop 1
	v_add_f32_dpp v16, v16, v16 quad_perm:[1,0,3,2] row_mask:0xf bank_mask:0xf
	global_store_dwordx2 v[54:55], v[20:21], off offset:1536
	v_or_b32_e32 v20, 7, v96
	v_add_u32_e32 v22, s10, v20
	v_ashrrev_i32_e32 v23, 31, v22
	s_waitcnt lgkmcnt(0)
	s_nop 1
	v_add_f32_dpp v16, v16, v16 quad_perm:[2,3,0,1] row_mask:0xf bank_mask:0xf
	v_lshlrev_b64 v[22:23], 11, v[22:23]
	v_lshl_add_u64 v[22:23], s[4:5], 0, v[22:23]
	s_add_i32 s10, s10, s18
	s_cmpk_gt_i32 s16, 0x2ff
	s_waitcnt lgkmcnt(0)
	s_nop 1
	v_add_f32_dpp v16, v16, v16 row_half_mirror row_mask:0xf bank_mask:0xf
	s_waitcnt lgkmcnt(0)
	s_nop 1
	v_add_f32_dpp v16, v16, v16 row_mirror row_mask:0xf bank_mask:0xf
	ds_bpermute_b32 v17, v100, v16
	s_waitcnt lgkmcnt(0)
	v_add_f32_e32 v16, v16, v17
	ds_bpermute_b32 v17, v101, v16
	s_waitcnt lgkmcnt(0)
	v_add_f32_e32 v16, v16, v17
	v_fmamk_f32 v16, v16, 0x3b000000, v166
	v_rsq_f32_e32 v16, v16
	s_nop 0
	v_pk_mul_f32 v[8:9], v[8:9], v[16:17] op_sel_hi:[1,0]
	s_nop 0
	v_pk_mul_f32 v[18:19], v[8:9], v[28:29]
	v_pk_mul_f32 v[8:9], v[14:15], v[16:17] op_sel_hi:[1,0]
	v_pk_mul_f32 v[12:13], v[12:13], v[16:17] op_sel_hi:[1,0]
	v_pk_mul_f32 v[14:15], v[8:9], v[30:31]
	v_pk_mul_f32 v[8:9], v[10:11], v[16:17] op_sel_hi:[1,0]
	v_pk_mul_f32 v[12:13], v[12:13], v[34:35]
	v_pk_mul_f32 v[16:17], v[8:9], v[24:25]
	v_cvt_pk_bf16_f32 v8, v12, v13
	v_cvt_pk_bf16_f32 v9, v14, v15
	v_cvt_pk_bf16_f32 v10, v18, v19
	v_cvt_pk_bf16_f32 v11, v16, v17
	v_lshl_add_u64 v[12:13], v[22:23], 0, v[48:49]
	global_store_dwordx4 v[12:13], v[8:11], off
	v_lshlrev_b32_e32 v12, 16, v50
	v_and_b32_e32 v13, 0xffff0000, v50
	v_lshlrev_b32_e32 v8, 16, v51
	v_and_b32_e32 v9, 0xffff0000, v51
	v_pk_mul_f32 v[14:15], v[12:13], v[12:13]
	v_pk_mul_f32 v[10:11], v[8:9], v[8:9]
	v_add_f32_e32 v14, v14, v15
	v_add_f32_e32 v10, v10, v14
	v_add_f32_e32 v10, v11, v10
	s_waitcnt lgkmcnt(0)
	s_nop 1
	v_add_f32_dpp v10, v10, v10 quad_perm:[1,0,3,2] row_mask:0xf bank_mask:0xf
	s_waitcnt lgkmcnt(0)
	s_nop 1
	v_add_f32_dpp v10, v10, v10 quad_perm:[2,3,0,1] row_mask:0xf bank_mask:0xf
	s_waitcnt lgkmcnt(0)
	s_nop 1
	v_add_f32_dpp v10, v10, v10 row_half_mirror row_mask:0xf bank_mask:0xf
	s_waitcnt lgkmcnt(0)
	s_nop 1
	v_add_f32_dpp v10, v10, v10 row_mirror row_mask:0xf bank_mask:0xf
	ds_bpermute_b32 v11, v100, v10
	s_waitcnt lgkmcnt(0)
	v_add_f32_e32 v10, v10, v11
	ds_bpermute_b32 v11, v101, v10
	s_waitcnt lgkmcnt(0)
	v_add_f32_e32 v10, v10, v11
	v_fmamk_f32 v10, v10, 0x3b800000, v166
	v_rsq_f32_e32 v10, v10
	s_nop 0
	v_pk_mul_f32 v[12:13], v[10:11], v[12:13] op_sel_hi:[0,1]
	v_pk_mul_f32 v[4:5], v[4:5], v[12:13]
	s_nop 0
	v_cvt_pk_bf16_f32 v12, v4, v5
	v_pk_mul_f32 v[4:5], v[10:11], v[8:9] op_sel_hi:[0,1]
	v_pk_mul_f32 v[4:5], v[6:7], v[4:5]
	v_mad_u64_u32 v[6:7], s[0:1], v20, s86, v[52:53]
	ds_read2_b32 v[8:9], v6 offset0:2 offset1:3
	ds_read2_b32 v[6:7], v6 offset1:1
	v_cvt_pk_bf16_f32 v13, v4, v5
	v_lshl_add_u64 v[4:5], v[22:23], 0, v[160:161]
	global_store_dwordx2 v[4:5], v[12:13], off offset:1024
	s_waitcnt lgkmcnt(1)
	v_pk_mul_f32 v[10:11], v[8:9], v[8:9]
	s_waitcnt lgkmcnt(0)
	v_pk_mul_f32 v[12:13], v[6:7], v[6:7]
	s_nop 0
	v_add_f32_e32 v12, v12, v13
	v_add_f32_e32 v10, v12, v10
	v_add_f32_e32 v10, v10, v11
	s_waitcnt lgkmcnt(0)
	s_nop 1
	v_add_f32_dpp v10, v10, v10 quad_perm:[1,0,3,2] row_mask:0xf bank_mask:0xf
	s_waitcnt lgkmcnt(0)
	s_nop 1
	v_add_f32_dpp v10, v10, v10 quad_perm:[2,3,0,1] row_mask:0xf bank_mask:0xf
	s_waitcnt lgkmcnt(0)
	s_nop 1
	v_add_f32_dpp v10, v10, v10 row_half_mirror row_mask:0xf bank_mask:0xf
	s_waitcnt lgkmcnt(0)
	s_nop 1
	v_add_f32_dpp v10, v10, v10 row_mirror row_mask:0xf bank_mask:0xf
	ds_bpermute_b32 v11, v100, v10
	s_waitcnt lgkmcnt(0)
	v_add_f32_e32 v10, v10, v11
	ds_bpermute_b32 v11, v101, v10
	s_waitcnt lgkmcnt(0)
	v_add_f32_e32 v10, v10, v11
	v_fmamk_f32 v10, v10, 0x3b800000, v166
	v_rsq_f32_e32 v10, v10
	s_nop 0
	v_pk_mul_f32 v[6:7], v[6:7], v[10:11] op_sel_hi:[1,0]
	s_nop 0
	v_pk_mul_f32 v[0:1], v[0:1], v[6:7]
	v_pk_mul_f32 v[6:7], v[8:9], v[10:11] op_sel_hi:[1,0]
	v_cvt_pk_bf16_f32 v0, v0, v1
	v_pk_mul_f32 v[2:3], v[2:3], v[6:7]
	s_nop 0
	v_cvt_pk_bf16_f32 v1, v2, v3
	global_store_dwordx2 v[4:5], v[0:1], off offset:1536
	s_barrier
	s_cbranch_scc0 .LBB0_588
